# v18: in the 6-DMA load segments of all GEMM loops the LDS-DMA instructions are issued before the 8 A-fragment ds_reads (disjoint LDS buffers), on top of v16
# baseline (speedup 1.0000x reference)
; #define PG8_STAGE(bufoff, gbase, voff) do { _Pragma("unroll") for (int _i = 0; _i < 2; ++_i) \
;         __builtin_amdgcn_global_load_lds((const unsigned*)((const char*)(gbase) + (voff)[_i]), (LAS unsigned*)(lds + (bufoff) + ldsw + _i * 8192), 16, 0, 0); } while (0)
; #define PG8_LDA(dst, b, h) do { _Pragma("unroll") for (int m = 0; m < 4; ++m) _Pragma("unroll") for (int k = 0; k < 2; ++k) dst[m][k] = *(const LAS bf16x8*)(lds + PG8_SA(b, h) + aoff + m * 2048 + k * 1024); } while (0)
; #define PG8_LDB(dst, b, h) do { _Pragma("unroll") for (int n = 0; n < 2; ++n) _Pragma("unroll") for (int k = 0; k < 2; ++k) dst[n][k] = *(const LAS bf16x8*)(lds + PG8_SB(b, h) + boff + n * 2048 + k * 1024); } while (0)
; #define PG8_MMA(ai, bj, At, Bt) do { __builtin_amdgcn_s_setprio(1); _Pragma("unroll") for (int m = 0; m < 4; ++m) _Pragma("unroll") for (int n = 0; n < 2; ++n) _Pragma("unroll") for (int k = 0; k < 2; ++k) \
;         acc[ai][bj][m][n] = __builtin_amdgcn_mfma_f32_16x16x32_bf16(Bt[n][k], At[m][k], acc[ai][bj][m][n], 0, 0, 0); __builtin_amdgcn_s_setprio(0); } while (0)
; #define PG8_WAIT_V(n) asm volatile("s_waitcnt vmcnt(" #n ")" ::: "memory")
; #define PG8_WAIT_L(n) asm volatile("s_waitcnt lgkmcnt(" #n ")" ::: "memory")
; #define PG8_BAR __builtin_amdgcn_s_barrier()
; #define PG8_SCHED __builtin_amdgcn_sched_barrier(0)
; template <class Epi, class Sched, bool ALIGN_EPI, bool SP2>
; __device__ __forceinline__ void gemm_phase(LAS unsigned char* lds, const Gemm g, const Sched& S, const Epi& E) {
;     ...
;             PG8_LDB(B0, 0, 0); PG8_LDB(B1, 0, 1); PG8_SCHED; PG8_LDA(At, 0, 0); PG8_STAGE(PG8_SA(1, 1), a1 + hstep, voffA);
;             PG8_WAIT_V(8); PG8_WAIT_L(0); PG8_BAR; PG8_MMA(0, 0, At, B0); PG8_MMA(0, 1, At, B1); PG8_BAR; PG8_SCHED;
;             PG8_LDA(At, 0, 1); PG8_STAGE(PG8_SB(0, 0), b2, voffB); PG8_STAGE(PG8_SB(0, 1), b2 + hstep, voffB); PG8_STAGE(PG8_SA(0, 0), a2, voffA);
;             PG8_WAIT_V(8); PG8_WAIT_L(0); PG8_BAR; PG8_MMA(1, 0, At, B0); PG8_MMA(1, 1, At, B1); PG8_BAR; PG8_SCHED;
.LBB0_216:
	ds_read_b128 v[128:131], v177
	ds_read_b128 v[132:135], v177 offset:1024
	ds_read_b128 v[136:139], v177 offset:2048
	ds_read_b128 v[140:143], v177 offset:3072
	ds_read_b128 v[168:171], v178
	ds_read_b128 v[184:187], v178 offset:1024
	ds_read_b128 v[188:191], v178 offset:2048
	ds_read_b128 v[192:195], v178 offset:3072
	s_add_u32 s8, s6, 0xfffc0080
	s_addc_u32 s9, s7, -1
	s_cmp_eq_u32 s43, 12
	s_cselect_b32 s11, s2, s9
	s_cselect_b32 s10, s3, s8
	s_cselect_b32 s9, s5, s42
	s_cselect_b32 s8, s12, s13
	s_add_i32 m0, s71, 0xc000
	ds_read_b128 v[196:199], v179
	ds_read_b128 v[200:203], v179 offset:1024
	ds_read_b128 v[204:207], v179 offset:2048
	ds_read_b128 v[208:211], v179 offset:3072
	ds_read_b128 v[212:215], v179 offset:4096
	ds_read_b128 v[216:219], v179 offset:5120
	ds_read_b128 v[220:223], v179 offset:6144
	ds_read_b128 v[224:227], v179 offset:7168
	global_load_lds_dwordx4 v160, s[6:7]
	s_add_i32 m0, s71, 0xe000
	s_nop 0
	global_load_lds_dwordx4 v162, s[6:7]
	s_waitcnt vmcnt(8)
	s_waitcnt lgkmcnt(0)
	s_barrier
	s_setprio 1
	s_waitcnt lgkmcnt(0)
	v_mfma_f32_16x16x32_bf16 v[124:127], v[128:131], v[196:199], v[124:127]
	v_mfma_f32_16x16x32_bf16 v[120:123], v[136:139], v[196:199], v[120:123]
	v_mfma_f32_16x16x32_bf16 v[116:119], v[128:131], v[204:207], v[116:119]
	v_mfma_f32_16x16x32_bf16 v[112:115], v[136:139], v[204:207], v[112:115]
	v_mfma_f32_16x16x32_bf16 v[108:111], v[128:131], v[212:215], v[108:111]
	v_mfma_f32_16x16x32_bf16 v[104:107], v[136:139], v[212:215], v[104:107]
	v_mfma_f32_16x16x32_bf16 v[100:103], v[128:131], v[220:223], v[100:103]
	v_mfma_f32_16x16x32_bf16 v[96:99], v[136:139], v[220:223], v[96:99]
	v_mfma_f32_16x16x32_bf16 v[124:127], v[132:135], v[200:203], v[124:127]
	v_mfma_f32_16x16x32_bf16 v[120:123], v[140:143], v[200:203], v[120:123]
	v_mfma_f32_16x16x32_bf16 v[116:119], v[132:135], v[208:211], v[116:119]
	v_mfma_f32_16x16x32_bf16 v[112:115], v[140:143], v[208:211], v[112:115]
	v_mfma_f32_16x16x32_bf16 v[108:111], v[132:135], v[216:219], v[108:111]
	v_mfma_f32_16x16x32_bf16 v[104:107], v[140:143], v[216:219], v[104:107]
	v_mfma_f32_16x16x32_bf16 v[100:103], v[132:135], v[224:227], v[100:103]
	v_mfma_f32_16x16x32_bf16 v[96:99], v[140:143], v[224:227], v[96:99]
	s_setprio 0
	s_setprio 1
	v_mfma_f32_16x16x32_bf16 v[60:63], v[168:171], v[196:199], v[60:63]
	v_mfma_f32_16x16x32_bf16 v[56:59], v[188:191], v[196:199], v[56:59]
	v_mfma_f32_16x16x32_bf16 v[52:55], v[168:171], v[204:207], v[52:55]
	v_mfma_f32_16x16x32_bf16 v[48:51], v[188:191], v[204:207], v[48:51]
	v_mfma_f32_16x16x32_bf16 v[44:47], v[168:171], v[212:215], v[44:47]
	v_mfma_f32_16x16x32_bf16 v[40:43], v[188:191], v[212:215], v[40:43]
	v_mfma_f32_16x16x32_bf16 v[36:39], v[168:171], v[220:223], v[36:39]
	v_mfma_f32_16x16x32_bf16 v[32:35], v[188:191], v[220:223], v[32:35]
	v_mfma_f32_16x16x32_bf16 v[60:63], v[184:187], v[200:203], v[60:63]
	v_mfma_f32_16x16x32_bf16 v[56:59], v[192:195], v[200:203], v[56:59]
	v_mfma_f32_16x16x32_bf16 v[52:55], v[184:187], v[208:211], v[52:55]
	v_mfma_f32_16x16x32_bf16 v[48:51], v[192:195], v[208:211], v[48:51]
	v_mfma_f32_16x16x32_bf16 v[44:47], v[184:187], v[216:219], v[44:47]
	v_mfma_f32_16x16x32_bf16 v[40:43], v[192:195], v[216:219], v[40:43]
	v_mfma_f32_16x16x32_bf16 v[36:39], v[184:187], v[224:227], v[36:39]
	v_mfma_f32_16x16x32_bf16 v[32:35], v[192:195], v[224:227], v[32:35]
	s_setprio 0
	s_barrier
	s_add_i32 s44, s74, s70
	s_mov_b32 m0, s44
	s_nop 0
	global_load_lds_dwordx4 v146, s[8:9]
	s_add_i32 m0, s44, 0x2000
	s_add_u32 s44, s8, 0x40000
	s_addc_u32 s45, s9, 0
	s_add_i32 s50, s75, s70
	global_load_lds_dwordx4 v150, s[8:9]
	s_mov_b32 m0, s50
	s_nop 0
	global_load_lds_dwordx4 v146, s[44:45]
	s_add_i32 m0, s50, 0x2000
	s_nop 0
	global_load_lds_dwordx4 v150, s[44:45]
	s_mov_b32 m0, s71
	s_nop 0
	global_load_lds_dwordx4 v144, s[10:11]
	s_mov_b32 m0, s72
	s_nop 0
	global_load_lds_dwordx4 v148, s[10:11]
	ds_read_b128 v[196:199], v179 offset:16384
	ds_read_b128 v[200:203], v179 offset:17408
	ds_read_b128 v[204:207], v179 offset:18432
	ds_read_b128 v[208:211], v179 offset:19456
	ds_read_b128 v[212:215], v179 offset:20480
	ds_read_b128 v[216:219], v179 offset:21504
	ds_read_b128 v[220:223], v179 offset:22528
	ds_read_b128 v[224:227], v179 offset:23552
	s_waitcnt vmcnt(8)
	s_waitcnt lgkmcnt(0)
	s_barrier
	s_setprio 1
	s_waitcnt lgkmcnt(0)
	v_mfma_f32_16x16x32_bf16 v[92:95], v[128:131], v[196:199], v[92:95]
	v_mfma_f32_16x16x32_bf16 v[88:91], v[136:139], v[196:199], v[88:91]
	v_mfma_f32_16x16x32_bf16 v[84:87], v[128:131], v[204:207], v[84:87]
	v_mfma_f32_16x16x32_bf16 v[80:83], v[136:139], v[204:207], v[80:83]
	v_mfma_f32_16x16x32_bf16 v[76:79], v[128:131], v[212:215], v[76:79]
	v_mfma_f32_16x16x32_bf16 v[72:75], v[136:139], v[212:215], v[72:75]
	v_mfma_f32_16x16x32_bf16 v[68:71], v[128:131], v[220:223], v[68:71]
	v_mfma_f32_16x16x32_bf16 v[64:67], v[136:139], v[220:223], v[64:67]
	v_mfma_f32_16x16x32_bf16 v[92:95], v[132:135], v[200:203], v[92:95]
	v_mfma_f32_16x16x32_bf16 v[88:91], v[140:143], v[200:203], v[88:91]
	v_mfma_f32_16x16x32_bf16 v[84:87], v[132:135], v[208:211], v[84:87]
	v_mfma_f32_16x16x32_bf16 v[80:83], v[140:143], v[208:211], v[80:83]
	v_mfma_f32_16x16x32_bf16 v[76:79], v[132:135], v[216:219], v[76:79]
	v_mfma_f32_16x16x32_bf16 v[72:75], v[140:143], v[216:219], v[72:75]
	v_mfma_f32_16x16x32_bf16 v[68:71], v[132:135], v[224:227], v[68:71]
	v_mfma_f32_16x16x32_bf16 v[64:67], v[140:143], v[224:227], v[64:67]
	s_setprio 0
	s_setprio 1
	v_mfma_f32_16x16x32_bf16 v[28:31], v[168:171], v[196:199], v[28:31]
	v_mfma_f32_16x16x32_bf16 v[24:27], v[188:191], v[196:199], v[24:27]
	v_mfma_f32_16x16x32_bf16 v[20:23], v[168:171], v[204:207], v[20:23]
	v_mfma_f32_16x16x32_bf16 v[16:19], v[188:191], v[204:207], v[16:19]
	v_mfma_f32_16x16x32_bf16 v[12:15], v[168:171], v[212:215], v[12:15]
	v_mfma_f32_16x16x32_bf16 v[8:11], v[188:191], v[212:215], v[8:11]
	v_mfma_f32_16x16x32_bf16 v[4:7], v[168:171], v[220:223], v[4:7]
	v_mfma_f32_16x16x32_bf16 v[0:3], v[188:191], v[220:223], v[0:3]
	v_mfma_f32_16x16x32_bf16 v[28:31], v[184:187], v[200:203], v[28:31]
	v_mfma_f32_16x16x32_bf16 v[24:27], v[192:195], v[200:203], v[24:27]
	v_mfma_f32_16x16x32_bf16 v[20:23], v[184:187], v[208:211], v[20:23]
	v_mfma_f32_16x16x32_bf16 v[16:19], v[192:195], v[208:211], v[16:19]
	v_mfma_f32_16x16x32_bf16 v[12:15], v[184:187], v[216:219], v[12:15]
	v_mfma_f32_16x16x32_bf16 v[8:11], v[192:195], v[216:219], v[8:11]
	v_mfma_f32_16x16x32_bf16 v[4:7], v[184:187], v[224:227], v[4:7]
	v_mfma_f32_16x16x32_bf16 v[0:3], v[192:195], v[224:227], v[0:3]
	s_setprio 0
	s_barrier
; #define PG8_STAGE(bufoff, gbase, voff) do { _Pragma("unroll") for (int _i = 0; _i < 2; ++_i) \
;         __builtin_amdgcn_global_load_lds((const unsigned*)((const char*)(gbase) + (voff)[_i]), (LAS unsigned*)(lds + (bufoff) + ldsw + _i * 8192), 16, 0, 0); } while (0)
; #define PG8_LDA(dst, b, h) do { _Pragma("unroll") for (int m = 0; m < 4; ++m) _Pragma("unroll") for (int k = 0; k < 2; ++k) dst[m][k] = *(const LAS bf16x8*)(lds + PG8_SA(b, h) + aoff + m * 2048 + k * 1024); } while (0)
; #define PG8_LDB(dst, b, h) do { _Pragma("unroll") for (int n = 0; n < 2; ++n) _Pragma("unroll") for (int k = 0; k < 2; ++k) dst[n][k] = *(const LAS bf16x8*)(lds + PG8_SB(b, h) + boff + n * 2048 + k * 1024); } while (0)
; #define PG8_MMA(ai, bj, At, Bt) do { __builtin_amdgcn_s_setprio(1); _Pragma("unroll") for (int m = 0; m < 4; ++m) _Pragma("unroll") for (int n = 0; n < 2; ++n) _Pragma("unroll") for (int k = 0; k < 2; ++k) \
;         acc[ai][bj][m][n] = __builtin_amdgcn_mfma_f32_16x16x32_bf16(Bt[n][k], At[m][k], acc[ai][bj][m][n], 0, 0, 0); __builtin_amdgcn_s_setprio(0); } while (0)
; #define PG8_WAIT_V(n) asm volatile("s_waitcnt vmcnt(" #n ")" ::: "memory")
; #define PG8_WAIT_L(n) asm volatile("s_waitcnt lgkmcnt(" #n ")" ::: "memory")
; #define PG8_BAR __builtin_amdgcn_s_barrier()
; #define PG8_SCHED __builtin_amdgcn_sched_barrier(0)
; template <class Epi, class Sched, bool ALIGN_EPI, bool SP2>
; __device__ __forceinline__ void gemm_phase(LAS unsigned char* lds, const Gemm g, const Sched& S, const Epi& E) {
;     ...
;             PG8_LDB(B0, 1, 0); PG8_LDB(B1, 1, 1); PG8_SCHED; PG8_LDA(At, 1, 0); PG8_STAGE(PG8_SA(0, 1), a2 + hstep, voffA);
;             PG8_WAIT_V(8); PG8_WAIT_L(0); PG8_BAR; PG8_MMA(0, 0, At, B0); PG8_MMA(0, 1, At, B1); PG8_BAR; PG8_SCHED;
;             PG8_LDA(At, 1, 1); PG8_STAGE(PG8_SB(1, 0), b3, voffB); PG8_STAGE(PG8_SB(1, 1), b3 + hstep, voffB); PG8_STAGE(PG8_SA(1, 0), a3, voffA);
;             PG8_WAIT_V(8); PG8_WAIT_L(0); PG8_BAR; PG8_MMA(1, 0, At, B0); PG8_MMA(1, 1, At, B1); PG8_BAR; PG8_SCHED;
;     __device__ __forceinline__ void operator()(const AccT& acc, const Unit& u, int wr, int wc, int fr, int fq) const {
;         const int pn = u.pn; const int row0 = u.pm * BM + wr * 64 + fr;
;         if (pn == 2) {
	s_add_i32 s44, 0, 0x18000
	s_add_i32 s45, 0, 0x1c000
	v_add_u32_e32 v140, s44, v174
	v_add_u32_e32 v152, s45, v174
	ds_read_b128 v[128:131], v140
	ds_read_b128 v[132:135], v140 offset:1024
	ds_read_b128 v[136:139], v140 offset:2048
	ds_read_b128 v[140:143], v140 offset:3072
	ds_read_b128 v[168:171], v152
	ds_read_b128 v[184:187], v152 offset:1024
	ds_read_b128 v[188:191], v152 offset:2048
	ds_read_b128 v[192:195], v152 offset:3072
	s_add_u32 s10, s10, 0x40000
	s_addc_u32 s11, s11, 0
	s_mov_b32 m0, s73
	ds_read_b128 v[196:199], v179 offset:32768
	ds_read_b128 v[200:203], v179 offset:33792
	ds_read_b128 v[204:207], v179 offset:34816
	ds_read_b128 v[208:211], v179 offset:35840
	ds_read_b128 v[212:215], v179 offset:36864
	ds_read_b128 v[216:219], v179 offset:37888
	ds_read_b128 v[220:223], v179 offset:38912
	ds_read_b128 v[224:227], v179 offset:39936
	global_load_lds_dwordx4 v144, s[10:11]
	s_mov_b32 m0, s82
	s_nop 0
	global_load_lds_dwordx4 v148, s[10:11]
	s_waitcnt vmcnt(8)
	s_waitcnt lgkmcnt(0)
	s_barrier
	s_setprio 1
	s_waitcnt lgkmcnt(0)
	v_mfma_f32_16x16x32_bf16 v[124:127], v[128:131], v[196:199], v[124:127]
	v_mfma_f32_16x16x32_bf16 v[120:123], v[136:139], v[196:199], v[120:123]
	v_mfma_f32_16x16x32_bf16 v[116:119], v[128:131], v[204:207], v[116:119]
	v_mfma_f32_16x16x32_bf16 v[112:115], v[136:139], v[204:207], v[112:115]
	v_mfma_f32_16x16x32_bf16 v[108:111], v[128:131], v[212:215], v[108:111]
	v_mfma_f32_16x16x32_bf16 v[104:107], v[136:139], v[212:215], v[104:107]
	v_mfma_f32_16x16x32_bf16 v[100:103], v[128:131], v[220:223], v[100:103]
	v_mfma_f32_16x16x32_bf16 v[96:99], v[136:139], v[220:223], v[96:99]
	v_mfma_f32_16x16x32_bf16 v[124:127], v[132:135], v[200:203], v[124:127]
	v_mfma_f32_16x16x32_bf16 v[120:123], v[140:143], v[200:203], v[120:123]
	v_mfma_f32_16x16x32_bf16 v[116:119], v[132:135], v[208:211], v[116:119]
	v_mfma_f32_16x16x32_bf16 v[112:115], v[140:143], v[208:211], v[112:115]
	v_mfma_f32_16x16x32_bf16 v[108:111], v[132:135], v[216:219], v[108:111]
	v_mfma_f32_16x16x32_bf16 v[104:107], v[140:143], v[216:219], v[104:107]
	v_mfma_f32_16x16x32_bf16 v[100:103], v[132:135], v[224:227], v[100:103]
	v_mfma_f32_16x16x32_bf16 v[96:99], v[140:143], v[224:227], v[96:99]
	s_setprio 0
	s_setprio 1
	v_mfma_f32_16x16x32_bf16 v[60:63], v[168:171], v[196:199], v[60:63]
	v_mfma_f32_16x16x32_bf16 v[56:59], v[188:191], v[196:199], v[56:59]
	v_mfma_f32_16x16x32_bf16 v[52:55], v[168:171], v[204:207], v[52:55]
	v_mfma_f32_16x16x32_bf16 v[48:51], v[188:191], v[204:207], v[48:51]
	v_mfma_f32_16x16x32_bf16 v[44:47], v[168:171], v[212:215], v[44:47]
	v_mfma_f32_16x16x32_bf16 v[40:43], v[188:191], v[212:215], v[40:43]
	v_mfma_f32_16x16x32_bf16 v[36:39], v[168:171], v[220:223], v[36:39]
	v_mfma_f32_16x16x32_bf16 v[32:35], v[188:191], v[220:223], v[32:35]
	v_mfma_f32_16x16x32_bf16 v[60:63], v[184:187], v[200:203], v[60:63]
	v_mfma_f32_16x16x32_bf16 v[56:59], v[192:195], v[200:203], v[56:59]
	v_mfma_f32_16x16x32_bf16 v[52:55], v[184:187], v[208:211], v[52:55]
	v_mfma_f32_16x16x32_bf16 v[48:51], v[192:195], v[208:211], v[48:51]
	v_mfma_f32_16x16x32_bf16 v[44:47], v[184:187], v[216:219], v[44:47]
	v_mfma_f32_16x16x32_bf16 v[40:43], v[192:195], v[216:219], v[40:43]
	v_mfma_f32_16x16x32_bf16 v[36:39], v[184:187], v[224:227], v[36:39]
	v_mfma_f32_16x16x32_bf16 v[32:35], v[192:195], v[224:227], v[32:35]
	s_setprio 0
	s_barrier
	s_add_u32 s100, s10, 0xfffc0080
	s_addc_u32 s101, s11, -1
	s_add_u32 s98, s8, 0x80
	s_addc_u32 s99, s9, 0
	s_add_i32 s10, s44, s70
	s_mov_b32 m0, s10
	s_nop 0
	global_load_lds_dwordx4 v146, s[98:99]
	s_add_i32 m0, s10, 0x2000
	s_add_u32 s8, s8, 0x40080
	s_addc_u32 s9, s9, 0
	s_add_i32 s10, s45, s70
	global_load_lds_dwordx4 v150, s[98:99]
	s_mov_b32 m0, s10
	s_nop 0
	global_load_lds_dwordx4 v146, s[8:9]
	s_add_i32 m0, s10, 0x2000
	s_nop 0
	global_load_lds_dwordx4 v150, s[8:9]
	s_mov_b32 m0, s83
	s_nop 0
	global_load_lds_dwordx4 v144, s[100:101]
	s_mov_b32 m0, s84
	s_nop 0
	global_load_lds_dwordx4 v148, s[100:101]
	ds_read_b128 v[196:199], v179 offset:49152
	ds_read_b128 v[200:203], v179 offset:50176
	ds_read_b128 v[204:207], v179 offset:51200
	ds_read_b128 v[208:211], v179 offset:52224
	ds_read_b128 v[212:215], v179 offset:53248
	ds_read_b128 v[216:219], v179 offset:54272
	ds_read_b128 v[220:223], v179 offset:55296
	ds_read_b128 v[224:227], v179 offset:56320
	s_waitcnt vmcnt(8)
	s_waitcnt lgkmcnt(0)
	s_barrier
	s_setprio 1
	s_waitcnt lgkmcnt(0)
	v_mfma_f32_16x16x32_bf16 v[92:95], v[128:131], v[196:199], v[92:95]
	v_mfma_f32_16x16x32_bf16 v[88:91], v[136:139], v[196:199], v[88:91]
	v_mfma_f32_16x16x32_bf16 v[84:87], v[128:131], v[204:207], v[84:87]
	v_mfma_f32_16x16x32_bf16 v[80:83], v[136:139], v[204:207], v[80:83]
	v_mfma_f32_16x16x32_bf16 v[76:79], v[128:131], v[212:215], v[76:79]
	v_mfma_f32_16x16x32_bf16 v[72:75], v[136:139], v[212:215], v[72:75]
	v_mfma_f32_16x16x32_bf16 v[68:71], v[128:131], v[220:223], v[68:71]
	v_mfma_f32_16x16x32_bf16 v[64:67], v[136:139], v[220:223], v[64:67]
	v_mfma_f32_16x16x32_bf16 v[92:95], v[132:135], v[200:203], v[92:95]
	v_mfma_f32_16x16x32_bf16 v[88:91], v[140:143], v[200:203], v[88:91]
	v_mfma_f32_16x16x32_bf16 v[84:87], v[132:135], v[208:211], v[84:87]
	v_mfma_f32_16x16x32_bf16 v[80:83], v[140:143], v[208:211], v[80:83]
	v_mfma_f32_16x16x32_bf16 v[76:79], v[132:135], v[216:219], v[76:79]
	v_mfma_f32_16x16x32_bf16 v[72:75], v[140:143], v[216:219], v[72:75]
	v_mfma_f32_16x16x32_bf16 v[68:71], v[132:135], v[224:227], v[68:71]
	v_mfma_f32_16x16x32_bf16 v[64:67], v[140:143], v[224:227], v[64:67]
	s_setprio 0
	s_setprio 1
	v_mfma_f32_16x16x32_bf16 v[28:31], v[168:171], v[196:199], v[28:31]
	v_mfma_f32_16x16x32_bf16 v[24:27], v[188:191], v[196:199], v[24:27]
	v_mfma_f32_16x16x32_bf16 v[20:23], v[168:171], v[204:207], v[20:23]
	v_mfma_f32_16x16x32_bf16 v[16:19], v[188:191], v[204:207], v[16:19]
	v_mfma_f32_16x16x32_bf16 v[12:15], v[168:171], v[212:215], v[12:15]
	v_mfma_f32_16x16x32_bf16 v[8:11], v[188:191], v[212:215], v[8:11]
	v_mfma_f32_16x16x32_bf16 v[4:7], v[168:171], v[220:223], v[4:7]
	v_mfma_f32_16x16x32_bf16 v[0:3], v[188:191], v[220:223], v[0:3]
	v_mfma_f32_16x16x32_bf16 v[28:31], v[184:187], v[200:203], v[28:31]
	v_mfma_f32_16x16x32_bf16 v[24:27], v[192:195], v[200:203], v[24:27]
	v_mfma_f32_16x16x32_bf16 v[20:23], v[184:187], v[208:211], v[20:23]
	v_mfma_f32_16x16x32_bf16 v[16:19], v[192:195], v[208:211], v[16:19]
	v_mfma_f32_16x16x32_bf16 v[12:15], v[184:187], v[216:219], v[12:15]
	v_mfma_f32_16x16x32_bf16 v[8:11], v[192:195], v[216:219], v[8:11]
	v_mfma_f32_16x16x32_bf16 v[4:7], v[184:187], v[224:227], v[4:7]
	v_mfma_f32_16x16x32_bf16 v[0:3], v[192:195], v[224:227], v[0:3]
	s_setprio 0
	s_barrier
	s_add_i32 s43, s43, 2
	s_add_u32 s6, s6, 0x100
	s_addc_u32 s7, s7, 0
	s_add_u32 s13, s13, 0x100
	s_addc_u32 s42, s42, 0
	s_cmp_gt_u32 s43, 13
	s_cbranch_scc0 .LBB0_216
	s_and_b64 vcc, exec, s[34:35]
	s_cbranch_vccnz .LBB0_221
	v_lshl_add_u32 v168, s4, 8, v155
	s_cmp_lg_u32 s16, 2
	s_mov_b64 s[4:5], -1
	s_cbranch_scc1 .LBB0_222

; #define PG8_STAGE(bufoff, gbase, voff) do { _Pragma("unroll") for (int _i = 0; _i < 2; ++_i) \
;         __builtin_amdgcn_global_load_lds((const unsigned*)((const char*)(gbase) + (voff)[_i]), (LAS unsigned*)(lds + (bufoff) + ldsw + _i * 8192), 16, 0, 0); } while (0)
; #define PG8_LDA(dst, b, h) do { _Pragma("unroll") for (int m = 0; m < 4; ++m) _Pragma("unroll") for (int k = 0; k < 2; ++k) dst[m][k] = *(const LAS bf16x8*)(lds + PG8_SA(b, h) + aoff + m * 2048 + k * 1024); } while (0)
; #define PG8_LDB(dst, b, h) do { _Pragma("unroll") for (int n = 0; n < 2; ++n) _Pragma("unroll") for (int k = 0; k < 2; ++k) dst[n][k] = *(const LAS bf16x8*)(lds + PG8_SB(b, h) + boff + n * 2048 + k * 1024); } while (0)
; #define PG8_MMA(ai, bj, At, Bt) do { __builtin_amdgcn_s_setprio(1); _Pragma("unroll") for (int m = 0; m < 4; ++m) _Pragma("unroll") for (int n = 0; n < 2; ++n) _Pragma("unroll") for (int k = 0; k < 2; ++k) \
;         acc[ai][bj][m][n] = __builtin_amdgcn_mfma_f32_16x16x32_bf16(Bt[n][k], At[m][k], acc[ai][bj][m][n], 0, 0, 0); __builtin_amdgcn_s_setprio(0); } while (0)
; #define PG8_WAIT_V(n) asm volatile("s_waitcnt vmcnt(" #n ")" ::: "memory")
; #define PG8_WAIT_L(n) asm volatile("s_waitcnt lgkmcnt(" #n ")" ::: "memory")
; #define PG8_BAR __builtin_amdgcn_s_barrier()
; #define PG8_SCHED __builtin_amdgcn_sched_barrier(0)
; template <class Epi, class Sched, bool ALIGN_EPI, bool SP2>
; __device__ __forceinline__ void gemm_phase(LAS unsigned char* lds, const Gemm g, const Sched& S, const Epi& E) {
;     ...
;             PG8_LDB(B0, 0, 0); PG8_LDB(B1, 0, 1); PG8_SCHED; PG8_LDA(At, 0, 0); PG8_STAGE(PG8_SA(1, 1), a1 + hstep, voffA);
;             PG8_WAIT_V(8); PG8_WAIT_L(0); PG8_BAR; PG8_MMA(0, 0, At, B0); PG8_MMA(0, 1, At, B1); PG8_BAR; PG8_SCHED;
;             PG8_LDA(At, 0, 1); PG8_STAGE(PG8_SB(0, 0), b2, voffB); PG8_STAGE(PG8_SB(0, 1), b2 + hstep, voffB); PG8_STAGE(PG8_SA(0, 0), a2, voffA);
;             PG8_WAIT_V(8); PG8_WAIT_L(0); PG8_BAR; PG8_MMA(1, 0, At, B0); PG8_MMA(1, 1, At, B1); PG8_BAR; PG8_SCHED;
.LBB0_293:
	ds_read_b128 v[152:155], v149
	ds_read_b128 v[156:159], v149 offset:1024
	ds_read_b128 v[160:163], v149 offset:2048
	ds_read_b128 v[164:167], v149 offset:3072
	ds_read_b128 v[168:171], v150
	ds_read_b128 v[176:179], v150 offset:1024
	ds_read_b128 v[180:183], v150 offset:2048
	ds_read_b128 v[184:187], v150 offset:3072
	s_add_u32 s36, s34, 0xfffc0080
	s_addc_u32 s37, s35, -1
	s_cmp_eq_u32 s62, 12
	s_cselect_b32 s39, s27, s37
	s_cselect_b32 s38, s58, s36
	s_cselect_b32 s37, s25, s61
	s_cselect_b32 s36, s59, s60
	s_add_i32 m0, s23, 0xc000
	ds_read_b128 v[188:191], v151
	ds_read_b128 v[192:195], v151 offset:1024
	ds_read_b128 v[196:199], v151 offset:2048
	ds_read_b128 v[200:203], v151 offset:3072
	ds_read_b128 v[204:207], v151 offset:4096
	ds_read_b128 v[208:211], v151 offset:5120
	ds_read_b128 v[212:215], v151 offset:6144
	ds_read_b128 v[216:219], v151 offset:7168
	global_load_lds_dwordx4 v138, s[34:35]
	s_add_i32 m0, s23, 0xe000
	s_nop 0
	global_load_lds_dwordx4 v140, s[34:35]
	s_waitcnt vmcnt(8)
	s_waitcnt lgkmcnt(0)
	s_barrier
	s_setprio 1
	s_waitcnt lgkmcnt(0)
	v_mfma_f32_16x16x32_bf16 v[124:127], v[152:155], v[188:191], v[124:127]
	v_mfma_f32_16x16x32_bf16 v[120:123], v[160:163], v[188:191], v[120:123]
	v_mfma_f32_16x16x32_bf16 v[116:119], v[152:155], v[196:199], v[116:119]
	v_mfma_f32_16x16x32_bf16 v[112:115], v[160:163], v[196:199], v[112:115]
	v_mfma_f32_16x16x32_bf16 v[100:103], v[152:155], v[204:207], v[100:103]
	v_mfma_f32_16x16x32_bf16 v[96:99], v[160:163], v[204:207], v[96:99]
	v_mfma_f32_16x16x32_bf16 v[84:87], v[152:155], v[212:215], v[84:87]
	v_mfma_f32_16x16x32_bf16 v[80:83], v[160:163], v[212:215], v[80:83]
	v_mfma_f32_16x16x32_bf16 v[124:127], v[156:159], v[192:195], v[124:127]
	v_mfma_f32_16x16x32_bf16 v[120:123], v[164:167], v[192:195], v[120:123]
	v_mfma_f32_16x16x32_bf16 v[116:119], v[156:159], v[200:203], v[116:119]
	v_mfma_f32_16x16x32_bf16 v[112:115], v[164:167], v[200:203], v[112:115]
	v_mfma_f32_16x16x32_bf16 v[100:103], v[156:159], v[208:211], v[100:103]
	v_mfma_f32_16x16x32_bf16 v[96:99], v[164:167], v[208:211], v[96:99]
	v_mfma_f32_16x16x32_bf16 v[84:87], v[156:159], v[216:219], v[84:87]
	v_mfma_f32_16x16x32_bf16 v[80:83], v[164:167], v[216:219], v[80:83]
	s_setprio 0
	s_setprio 1
	v_mfma_f32_16x16x32_bf16 v[108:111], v[168:171], v[188:191], v[108:111]
	v_mfma_f32_16x16x32_bf16 v[104:107], v[180:183], v[188:191], v[104:107]
	v_mfma_f32_16x16x32_bf16 v[92:95], v[168:171], v[196:199], v[92:95]
	v_mfma_f32_16x16x32_bf16 v[88:91], v[180:183], v[196:199], v[88:91]
	v_mfma_f32_16x16x32_bf16 v[76:79], v[168:171], v[204:207], v[76:79]
	v_mfma_f32_16x16x32_bf16 v[72:75], v[180:183], v[204:207], v[72:75]
	v_mfma_f32_16x16x32_bf16 v[68:71], v[168:171], v[212:215], v[68:71]
	v_mfma_f32_16x16x32_bf16 v[64:67], v[180:183], v[212:215], v[64:67]
	v_mfma_f32_16x16x32_bf16 v[108:111], v[176:179], v[192:195], v[108:111]
	v_mfma_f32_16x16x32_bf16 v[104:107], v[184:187], v[192:195], v[104:107]
	v_mfma_f32_16x16x32_bf16 v[92:95], v[176:179], v[200:203], v[92:95]
	v_mfma_f32_16x16x32_bf16 v[88:91], v[184:187], v[200:203], v[88:91]
	v_mfma_f32_16x16x32_bf16 v[76:79], v[176:179], v[208:211], v[76:79]
	v_mfma_f32_16x16x32_bf16 v[72:75], v[184:187], v[208:211], v[72:75]
	v_mfma_f32_16x16x32_bf16 v[68:71], v[176:179], v[216:219], v[68:71]
	v_mfma_f32_16x16x32_bf16 v[64:67], v[184:187], v[216:219], v[64:67]
	s_setprio 0
	s_barrier
	s_add_i32 s63, s50, s33
	s_mov_b32 m0, s63
	s_nop 0
	global_load_lds_dwordx4 v130, s[36:37]
	s_add_i32 m0, s63, 0x2000
	s_add_u32 s64, s36, 0x40000
	s_addc_u32 s65, s37, 0
	s_add_i32 s63, s51, s33
	global_load_lds_dwordx4 v134, s[36:37]
	s_mov_b32 m0, s63
	s_nop 0
	global_load_lds_dwordx4 v130, s[64:65]
	s_add_i32 m0, s63, 0x2000
	s_nop 0
	global_load_lds_dwordx4 v134, s[64:65]
	s_mov_b32 m0, s23
	s_nop 0
	global_load_lds_dwordx4 v128, s[38:39]
	s_mov_b32 m0, s42
	s_nop 0
	global_load_lds_dwordx4 v132, s[38:39]
	ds_read_b128 v[188:191], v151 offset:16384
	ds_read_b128 v[192:195], v151 offset:17408
	ds_read_b128 v[196:199], v151 offset:18432
	ds_read_b128 v[200:203], v151 offset:19456
	ds_read_b128 v[204:207], v151 offset:20480
	ds_read_b128 v[208:211], v151 offset:21504
	ds_read_b128 v[212:215], v151 offset:22528
	ds_read_b128 v[216:219], v151 offset:23552
	s_waitcnt vmcnt(8)
	s_waitcnt lgkmcnt(0)
	s_barrier
	s_setprio 1
	s_waitcnt lgkmcnt(0)
	v_mfma_f32_16x16x32_bf16 v[60:63], v[152:155], v[188:191], v[60:63]
	v_mfma_f32_16x16x32_bf16 v[56:59], v[160:163], v[188:191], v[56:59]
	v_mfma_f32_16x16x32_bf16 v[52:55], v[152:155], v[196:199], v[52:55]
	v_mfma_f32_16x16x32_bf16 v[48:51], v[160:163], v[196:199], v[48:51]
	v_mfma_f32_16x16x32_bf16 v[36:39], v[152:155], v[204:207], v[36:39]
	v_mfma_f32_16x16x32_bf16 v[32:35], v[160:163], v[204:207], v[32:35]
	v_mfma_f32_16x16x32_bf16 v[20:23], v[152:155], v[212:215], v[20:23]
	v_mfma_f32_16x16x32_bf16 v[16:19], v[160:163], v[212:215], v[16:19]
	v_mfma_f32_16x16x32_bf16 v[60:63], v[156:159], v[192:195], v[60:63]
	v_mfma_f32_16x16x32_bf16 v[56:59], v[164:167], v[192:195], v[56:59]
	v_mfma_f32_16x16x32_bf16 v[52:55], v[156:159], v[200:203], v[52:55]
	v_mfma_f32_16x16x32_bf16 v[48:51], v[164:167], v[200:203], v[48:51]
	v_mfma_f32_16x16x32_bf16 v[36:39], v[156:159], v[208:211], v[36:39]
	v_mfma_f32_16x16x32_bf16 v[32:35], v[164:167], v[208:211], v[32:35]
	v_mfma_f32_16x16x32_bf16 v[20:23], v[156:159], v[216:219], v[20:23]
	v_mfma_f32_16x16x32_bf16 v[16:19], v[164:167], v[216:219], v[16:19]
	s_setprio 0
	s_setprio 1
	v_mfma_f32_16x16x32_bf16 v[44:47], v[168:171], v[188:191], v[44:47]
	v_mfma_f32_16x16x32_bf16 v[40:43], v[180:183], v[188:191], v[40:43]
	v_mfma_f32_16x16x32_bf16 v[28:31], v[168:171], v[196:199], v[28:31]
	v_mfma_f32_16x16x32_bf16 v[24:27], v[180:183], v[196:199], v[24:27]
	v_mfma_f32_16x16x32_bf16 v[12:15], v[168:171], v[204:207], v[12:15]
	v_mfma_f32_16x16x32_bf16 v[8:11], v[180:183], v[204:207], v[8:11]
	v_mfma_f32_16x16x32_bf16 v[4:7], v[168:171], v[212:215], v[4:7]
	v_mfma_f32_16x16x32_bf16 v[0:3], v[180:183], v[212:215], v[0:3]
	v_mfma_f32_16x16x32_bf16 v[44:47], v[176:179], v[192:195], v[44:47]
	v_mfma_f32_16x16x32_bf16 v[40:43], v[184:187], v[192:195], v[40:43]
	v_mfma_f32_16x16x32_bf16 v[28:31], v[176:179], v[200:203], v[28:31]
	v_mfma_f32_16x16x32_bf16 v[24:27], v[184:187], v[200:203], v[24:27]
	v_mfma_f32_16x16x32_bf16 v[12:15], v[176:179], v[208:211], v[12:15]
	v_mfma_f32_16x16x32_bf16 v[8:11], v[184:187], v[208:211], v[8:11]
	v_mfma_f32_16x16x32_bf16 v[4:7], v[176:179], v[216:219], v[4:7]
	v_mfma_f32_16x16x32_bf16 v[0:3], v[184:187], v[216:219], v[0:3]
	s_setprio 0
	s_barrier
; #define PG8_STAGE(bufoff, gbase, voff) do { _Pragma("unroll") for (int _i = 0; _i < 2; ++_i) \
;         __builtin_amdgcn_global_load_lds((const unsigned*)((const char*)(gbase) + (voff)[_i]), (LAS unsigned*)(lds + (bufoff) + ldsw + _i * 8192), 16, 0, 0); } while (0)
; #define PG8_LDA(dst, b, h) do { _Pragma("unroll") for (int m = 0; m < 4; ++m) _Pragma("unroll") for (int k = 0; k < 2; ++k) dst[m][k] = *(const LAS bf16x8*)(lds + PG8_SA(b, h) + aoff + m * 2048 + k * 1024); } while (0)
; #define PG8_LDB(dst, b, h) do { _Pragma("unroll") for (int n = 0; n < 2; ++n) _Pragma("unroll") for (int k = 0; k < 2; ++k) dst[n][k] = *(const LAS bf16x8*)(lds + PG8_SB(b, h) + boff + n * 2048 + k * 1024); } while (0)
; #define PG8_MMA(ai, bj, At, Bt) do { __builtin_amdgcn_s_setprio(1); _Pragma("unroll") for (int m = 0; m < 4; ++m) _Pragma("unroll") for (int n = 0; n < 2; ++n) _Pragma("unroll") for (int k = 0; k < 2; ++k) \
;         acc[ai][bj][m][n] = __builtin_amdgcn_mfma_f32_16x16x32_bf16(Bt[n][k], At[m][k], acc[ai][bj][m][n], 0, 0, 0); __builtin_amdgcn_s_setprio(0); } while (0)
; #define PG8_WAIT_V(n) asm volatile("s_waitcnt vmcnt(" #n ")" ::: "memory")
; #define PG8_WAIT_L(n) asm volatile("s_waitcnt lgkmcnt(" #n ")" ::: "memory")
; #define PG8_BAR __builtin_amdgcn_s_barrier()
; #define PG8_SCHED __builtin_amdgcn_sched_barrier(0)
; template <class Epi, class Sched, bool ALIGN_EPI, bool SP2>
; __device__ __forceinline__ void gemm_phase(LAS unsigned char* lds, const Gemm g, const Sched& S, const Epi& E) {
;     ...
;             PG8_LDB(B0, 1, 0); PG8_LDB(B1, 1, 1); PG8_SCHED; PG8_LDA(At, 1, 0); PG8_STAGE(PG8_SA(0, 1), a2 + hstep, voffA);
;             PG8_WAIT_V(8); PG8_WAIT_L(0); PG8_BAR; PG8_MMA(0, 0, At, B0); PG8_MMA(0, 1, At, B1); PG8_BAR; PG8_SCHED;
	s_add_i32 s63, 0, 0x18000
	v_add_u32_e32 v136, s63, v147
	s_add_i32 s64, 0, 0x1c000
	ds_read_b128 v[152:155], v136
	ds_read_b128 v[156:159], v136 offset:1024
	ds_read_b128 v[160:163], v136 offset:2048
	ds_read_b128 v[164:167], v136 offset:3072
	v_add_u32_e32 v136, s64, v147
	ds_read_b128 v[168:171], v136
	ds_read_b128 v[176:179], v136 offset:1024
	ds_read_b128 v[180:183], v136 offset:2048
	ds_read_b128 v[184:187], v136 offset:3072
	s_add_u32 s38, s38, 0x40000
	s_addc_u32 s39, s39, 0
	s_mov_b32 m0, s43
	ds_read_b128 v[188:191], v151 offset:32768
	ds_read_b128 v[192:195], v151 offset:33792
	ds_read_b128 v[196:199], v151 offset:34816
	ds_read_b128 v[200:203], v151 offset:35840
	ds_read_b128 v[204:207], v151 offset:36864
	ds_read_b128 v[208:211], v151 offset:37888
	ds_read_b128 v[212:215], v151 offset:38912
	ds_read_b128 v[216:219], v151 offset:39936
	global_load_lds_dwordx4 v128, s[38:39]
	s_mov_b32 m0, s44
	s_nop 0
	global_load_lds_dwordx4 v132, s[38:39]
	s_waitcnt vmcnt(8)
	s_waitcnt lgkmcnt(0)
	s_barrier
	s_setprio 1
	s_waitcnt lgkmcnt(0)
	v_mfma_f32_16x16x32_bf16 v[124:127], v[152:155], v[188:191], v[124:127]
	v_mfma_f32_16x16x32_bf16 v[120:123], v[160:163], v[188:191], v[120:123]
	v_mfma_f32_16x16x32_bf16 v[116:119], v[152:155], v[196:199], v[116:119]
	v_mfma_f32_16x16x32_bf16 v[112:115], v[160:163], v[196:199], v[112:115]
	v_mfma_f32_16x16x32_bf16 v[100:103], v[152:155], v[204:207], v[100:103]
	v_mfma_f32_16x16x32_bf16 v[96:99], v[160:163], v[204:207], v[96:99]
	v_mfma_f32_16x16x32_bf16 v[84:87], v[152:155], v[212:215], v[84:87]
	v_mfma_f32_16x16x32_bf16 v[80:83], v[160:163], v[212:215], v[80:83]
	v_mfma_f32_16x16x32_bf16 v[124:127], v[156:159], v[192:195], v[124:127]
	v_mfma_f32_16x16x32_bf16 v[120:123], v[164:167], v[192:195], v[120:123]
	v_mfma_f32_16x16x32_bf16 v[116:119], v[156:159], v[200:203], v[116:119]
	v_mfma_f32_16x16x32_bf16 v[112:115], v[164:167], v[200:203], v[112:115]
	v_mfma_f32_16x16x32_bf16 v[100:103], v[156:159], v[208:211], v[100:103]
	v_mfma_f32_16x16x32_bf16 v[96:99], v[164:167], v[208:211], v[96:99]
	v_mfma_f32_16x16x32_bf16 v[84:87], v[156:159], v[216:219], v[84:87]
	v_mfma_f32_16x16x32_bf16 v[80:83], v[164:167], v[216:219], v[80:83]
	s_setprio 0
	s_setprio 1
	v_mfma_f32_16x16x32_bf16 v[108:111], v[168:171], v[188:191], v[108:111]
	v_mfma_f32_16x16x32_bf16 v[104:107], v[180:183], v[188:191], v[104:107]
	v_mfma_f32_16x16x32_bf16 v[92:95], v[168:171], v[196:199], v[92:95]
	v_mfma_f32_16x16x32_bf16 v[88:91], v[180:183], v[196:199], v[88:91]
	v_mfma_f32_16x16x32_bf16 v[76:79], v[168:171], v[204:207], v[76:79]
	v_mfma_f32_16x16x32_bf16 v[72:75], v[180:183], v[204:207], v[72:75]
	v_mfma_f32_16x16x32_bf16 v[68:71], v[168:171], v[212:215], v[68:71]
	v_mfma_f32_16x16x32_bf16 v[64:67], v[180:183], v[212:215], v[64:67]
	v_mfma_f32_16x16x32_bf16 v[108:111], v[176:179], v[192:195], v[108:111]
	v_mfma_f32_16x16x32_bf16 v[104:107], v[184:187], v[192:195], v[104:107]
	v_mfma_f32_16x16x32_bf16 v[92:95], v[176:179], v[200:203], v[92:95]
	v_mfma_f32_16x16x32_bf16 v[88:91], v[184:187], v[200:203], v[88:91]
	v_mfma_f32_16x16x32_bf16 v[76:79], v[176:179], v[208:211], v[76:79]
	v_mfma_f32_16x16x32_bf16 v[72:75], v[184:187], v[208:211], v[72:75]
	v_mfma_f32_16x16x32_bf16 v[68:71], v[176:179], v[216:219], v[68:71]
	v_mfma_f32_16x16x32_bf16 v[64:67], v[184:187], v[216:219], v[64:67]
	s_setprio 0
	s_barrier
; #define PG8_STAGE(bufoff, gbase, voff) do { _Pragma("unroll") for (int _i = 0; _i < 2; ++_i) \
;         __builtin_amdgcn_global_load_lds((const unsigned*)((const char*)(gbase) + (voff)[_i]), (LAS unsigned*)(lds + (bufoff) + ldsw + _i * 8192), 16, 0, 0); } while (0)
; #define PG8_LDA(dst, b, h) do { _Pragma("unroll") for (int m = 0; m < 4; ++m) _Pragma("unroll") for (int k = 0; k < 2; ++k) dst[m][k] = *(const LAS bf16x8*)(lds + PG8_SA(b, h) + aoff + m * 2048 + k * 1024); } while (0)
; #define PG8_MMA(ai, bj, At, Bt) do { __builtin_amdgcn_s_setprio(1); _Pragma("unroll") for (int m = 0; m < 4; ++m) _Pragma("unroll") for (int n = 0; n < 2; ++n) _Pragma("unroll") for (int k = 0; k < 2; ++k) \
;         acc[ai][bj][m][n] = __builtin_amdgcn_mfma_f32_16x16x32_bf16(Bt[n][k], At[m][k], acc[ai][bj][m][n], 0, 0, 0); __builtin_amdgcn_s_setprio(0); } while (0)
; #define PG8_WAIT_V(n) asm volatile("s_waitcnt vmcnt(" #n ")" ::: "memory")
; #define PG8_WAIT_L(n) asm volatile("s_waitcnt lgkmcnt(" #n ")" ::: "memory")
; #define PG8_BAR __builtin_amdgcn_s_barrier()
; #define PG8_SCHED __builtin_amdgcn_sched_barrier(0)
; template <class Epi, class Sched, bool ALIGN_EPI, bool SP2>
; __device__ __forceinline__ void gemm_phase(LAS unsigned char* lds, const Gemm g, const Sched& S, const Epi& E) {
;     ...
;             PG8_LDA(At, 1, 1); PG8_STAGE(PG8_SB(1, 0), b3, voffB); PG8_STAGE(PG8_SB(1, 1), b3 + hstep, voffB); PG8_STAGE(PG8_SA(1, 0), a3, voffA);
;             PG8_WAIT_V(8); PG8_WAIT_L(0); PG8_BAR; PG8_MMA(1, 0, At, B0); PG8_MMA(1, 1, At, B1); PG8_BAR; PG8_SCHED;
;     ...
;         if constexpr (ALIGN_EPI) { if (wr == 0) PG8_BAR; }
;         bool keep = false;
;         if constexpr (Epi::DUAL) { if (cur.seg == 0) { E.mid(acc, cur, wr, wc, fr, fq); keep = true; } }
;         if (!keep) E(acc, cur, wr, wc, fr, fq);
	s_add_u32 s100, s38, 0xfffc0080
	s_addc_u32 s101, s39, -1
	s_add_u32 s98, s36, 0x80
	s_addc_u32 s99, s37, 0
	s_add_i32 s38, s63, s33
	s_mov_b32 m0, s38
	s_nop 0
	global_load_lds_dwordx4 v130, s[98:99]
	s_add_i32 m0, s38, 0x2000
	s_add_u32 s36, s36, 0x40080
	s_addc_u32 s37, s37, 0
	s_add_i32 s38, s64, s33
	global_load_lds_dwordx4 v134, s[98:99]
	s_mov_b32 m0, s38
	s_nop 0
	global_load_lds_dwordx4 v130, s[36:37]
	s_add_i32 m0, s38, 0x2000
	s_nop 0
	global_load_lds_dwordx4 v134, s[36:37]
	s_mov_b32 m0, s46
	s_nop 0
	global_load_lds_dwordx4 v128, s[100:101]
	s_mov_b32 m0, s47
	s_nop 0
	global_load_lds_dwordx4 v132, s[100:101]
	ds_read_b128 v[188:191], v151 offset:49152
	ds_read_b128 v[192:195], v151 offset:50176
	ds_read_b128 v[196:199], v151 offset:51200
	ds_read_b128 v[200:203], v151 offset:52224
	ds_read_b128 v[204:207], v151 offset:53248
	ds_read_b128 v[208:211], v151 offset:54272
	ds_read_b128 v[212:215], v151 offset:55296
	ds_read_b128 v[216:219], v151 offset:56320
	s_waitcnt vmcnt(8)
	s_waitcnt lgkmcnt(0)
	s_barrier
	s_setprio 1
	s_waitcnt lgkmcnt(0)
	v_mfma_f32_16x16x32_bf16 v[60:63], v[152:155], v[188:191], v[60:63]
	v_mfma_f32_16x16x32_bf16 v[56:59], v[160:163], v[188:191], v[56:59]
	v_mfma_f32_16x16x32_bf16 v[52:55], v[152:155], v[196:199], v[52:55]
	v_mfma_f32_16x16x32_bf16 v[48:51], v[160:163], v[196:199], v[48:51]
	v_mfma_f32_16x16x32_bf16 v[36:39], v[152:155], v[204:207], v[36:39]
	v_mfma_f32_16x16x32_bf16 v[32:35], v[160:163], v[204:207], v[32:35]
	v_mfma_f32_16x16x32_bf16 v[20:23], v[152:155], v[212:215], v[20:23]
	v_mfma_f32_16x16x32_bf16 v[16:19], v[160:163], v[212:215], v[16:19]
	v_mfma_f32_16x16x32_bf16 v[60:63], v[156:159], v[192:195], v[60:63]
	v_mfma_f32_16x16x32_bf16 v[56:59], v[164:167], v[192:195], v[56:59]
	v_mfma_f32_16x16x32_bf16 v[52:55], v[156:159], v[200:203], v[52:55]
	v_mfma_f32_16x16x32_bf16 v[48:51], v[164:167], v[200:203], v[48:51]
	v_mfma_f32_16x16x32_bf16 v[36:39], v[156:159], v[208:211], v[36:39]
	v_mfma_f32_16x16x32_bf16 v[32:35], v[164:167], v[208:211], v[32:35]
	v_mfma_f32_16x16x32_bf16 v[20:23], v[156:159], v[216:219], v[20:23]
	v_mfma_f32_16x16x32_bf16 v[16:19], v[164:167], v[216:219], v[16:19]
	s_setprio 0
	s_setprio 1
	v_mfma_f32_16x16x32_bf16 v[44:47], v[168:171], v[188:191], v[44:47]
	v_mfma_f32_16x16x32_bf16 v[40:43], v[180:183], v[188:191], v[40:43]
	v_mfma_f32_16x16x32_bf16 v[28:31], v[168:171], v[196:199], v[28:31]
	v_mfma_f32_16x16x32_bf16 v[24:27], v[180:183], v[196:199], v[24:27]
	v_mfma_f32_16x16x32_bf16 v[12:15], v[168:171], v[204:207], v[12:15]
	v_mfma_f32_16x16x32_bf16 v[8:11], v[180:183], v[204:207], v[8:11]
	v_mfma_f32_16x16x32_bf16 v[4:7], v[168:171], v[212:215], v[4:7]
	v_mfma_f32_16x16x32_bf16 v[0:3], v[180:183], v[212:215], v[0:3]
	v_mfma_f32_16x16x32_bf16 v[44:47], v[176:179], v[192:195], v[44:47]
	v_mfma_f32_16x16x32_bf16 v[40:43], v[184:187], v[192:195], v[40:43]
	v_mfma_f32_16x16x32_bf16 v[28:31], v[176:179], v[200:203], v[28:31]
	v_mfma_f32_16x16x32_bf16 v[24:27], v[184:187], v[200:203], v[24:27]
	v_mfma_f32_16x16x32_bf16 v[12:15], v[176:179], v[208:211], v[12:15]
	v_mfma_f32_16x16x32_bf16 v[8:11], v[184:187], v[208:211], v[8:11]
	v_mfma_f32_16x16x32_bf16 v[4:7], v[176:179], v[216:219], v[4:7]
	v_mfma_f32_16x16x32_bf16 v[0:3], v[184:187], v[216:219], v[0:3]
	s_setprio 0
	s_barrier
	s_add_i32 s62, s62, 2
	s_add_u32 s34, s34, 0x100
	s_addc_u32 s35, s35, 0
	s_add_u32 s60, s60, 0x100
	s_addc_u32 s61, s61, 0
	s_cmp_gt_u32 s62, 13
	s_cbranch_scc0 .LBB0_293
	v_readlane_b32 s60, v236, 28
	v_readlane_b32 s64, v236, 32
	v_readlane_b32 s65, v236, 33
	v_readlane_b32 s66, v236, 34
	v_readlane_b32 s67, v236, 35
	v_readlane_b32 s72, v236, 40
	v_readlane_b32 s73, v236, 41
	v_readlane_b32 s74, v236, 42
	v_readlane_b32 s75, v236, 43
	s_mov_b64 s[58:59], s[66:67]
	s_mov_b64 s[64:65], s[72:73]
	s_and_b64 vcc, exec, s[10:11]
	s_mov_b64 s[66:67], s[74:75]
	v_readlane_b32 s61, v236, 29
	v_readlane_b32 s62, v236, 30
	v_readlane_b32 s63, v236, 31
	v_readlane_b32 s68, v236, 36
	v_readlane_b32 s69, v236, 37
	v_readlane_b32 s70, v236, 38
	v_readlane_b32 s71, v236, 39
	s_cbranch_vccz .LBB0_296
	s_barrier

; #define PG8_STAGE(bufoff, gbase, voff) do { _Pragma("unroll") for (int _i = 0; _i < 2; ++_i) \
;         __builtin_amdgcn_global_load_lds((const unsigned*)((const char*)(gbase) + (voff)[_i]), (LAS unsigned*)(lds + (bufoff) + ldsw + _i * 8192), 16, 0, 0); } while (0)
; #define PG8_LDA(dst, b, h) do { _Pragma("unroll") for (int m = 0; m < 4; ++m) _Pragma("unroll") for (int k = 0; k < 2; ++k) dst[m][k] = *(const LAS bf16x8*)(lds + PG8_SA(b, h) + aoff + m * 2048 + k * 1024); } while (0)
; #define PG8_LDB(dst, b, h) do { _Pragma("unroll") for (int n = 0; n < 2; ++n) _Pragma("unroll") for (int k = 0; k < 2; ++k) dst[n][k] = *(const LAS bf16x8*)(lds + PG8_SB(b, h) + boff + n * 2048 + k * 1024); } while (0)
; #define PG8_MMA(ai, bj, At, Bt) do { __builtin_amdgcn_s_setprio(1); _Pragma("unroll") for (int m = 0; m < 4; ++m) _Pragma("unroll") for (int n = 0; n < 2; ++n) _Pragma("unroll") for (int k = 0; k < 2; ++k) \
;         acc[ai][bj][m][n] = __builtin_amdgcn_mfma_f32_16x16x32_bf16(Bt[n][k], At[m][k], acc[ai][bj][m][n], 0, 0, 0); __builtin_amdgcn_s_setprio(0); } while (0)
; #define PG8_WAIT_V(n) asm volatile("s_waitcnt vmcnt(" #n ")" ::: "memory")
; #define PG8_WAIT_L(n) asm volatile("s_waitcnt lgkmcnt(" #n ")" ::: "memory")
; #define PG8_BAR __builtin_amdgcn_s_barrier()
; #define PG8_SCHED __builtin_amdgcn_sched_barrier(0)
; template <class Epi, class Sched, bool ALIGN_EPI, bool SP2>
; __device__ __forceinline__ void gemm_phase(LAS unsigned char* lds, const Gemm g, const Sched& S, const Epi& E) {
;     ...
;             PG8_LDB(B0, 0, 0); PG8_LDB(B1, 0, 1); PG8_SCHED; PG8_LDA(At, 0, 0); PG8_STAGE(PG8_SA(1, 1), a1 + hstep, voffA);
;             PG8_WAIT_V(8); PG8_WAIT_L(0); PG8_BAR; PG8_MMA(0, 0, At, B0); PG8_MMA(0, 1, At, B1); PG8_BAR; PG8_SCHED;
;             PG8_LDA(At, 0, 1); PG8_STAGE(PG8_SB(0, 0), b2, voffB); PG8_STAGE(PG8_SB(0, 1), b2 + hstep, voffB); PG8_STAGE(PG8_SA(0, 0), a2, voffA);
;             PG8_WAIT_V(8); PG8_WAIT_L(0); PG8_BAR; PG8_MMA(1, 0, At, B0); PG8_MMA(1, 1, At, B1); PG8_BAR; PG8_SCHED;
.LBB0_468:
	v_add_u32_e32 v140, s62, v187
	v_add_u32_e32 v156, s63, v187
	ds_read_b128 v[128:131], v140
	ds_read_b128 v[132:135], v140 offset:1024
	ds_read_b128 v[136:139], v140 offset:2048
	ds_read_b128 v[140:143], v140 offset:3072
	ds_read_b128 v[144:147], v156
	ds_read_b128 v[148:151], v156 offset:1024
	ds_read_b128 v[152:155], v156 offset:2048
	ds_read_b128 v[156:159], v156 offset:3072
	s_add_u32 s34, s28, 0xfffe0080
	s_addc_u32 s35, s29, -1
	s_cmp_eq_u32 s58, 4
	s_cselect_b32 s37, s21, s35
	s_cselect_b32 s36, s50, s34
	s_cselect_b32 s35, s23, s57
	s_cselect_b32 s34, s51, s56
	s_add_i32 m0, s43, 0xc000
	ds_read_b128 v[160:163], v188
	ds_read_b128 v[190:193], v188 offset:1024
	ds_read_b128 v[194:197], v188 offset:2048
	ds_read_b128 v[198:201], v188 offset:3072
	ds_read_b128 v[202:205], v188 offset:4096
	ds_read_b128 v[206:209], v188 offset:5120
	ds_read_b128 v[210:213], v188 offset:6144
	ds_read_b128 v[214:217], v188 offset:7168
	global_load_lds_dwordx4 v176, s[28:29]
	s_add_i32 m0, s43, 0xe000
	s_nop 0
	global_load_lds_dwordx4 v178, s[28:29]
	s_waitcnt vmcnt(8)
	s_waitcnt lgkmcnt(0)
	s_barrier
	s_setprio 1
	s_waitcnt lgkmcnt(0)
	v_mfma_f32_16x16x32_bf16 v[124:127], v[128:131], v[160:163], v[124:127]
	v_mfma_f32_16x16x32_bf16 v[120:123], v[136:139], v[160:163], v[120:123]
	v_mfma_f32_16x16x32_bf16 v[116:119], v[128:131], v[194:197], v[116:119]
	v_mfma_f32_16x16x32_bf16 v[112:115], v[136:139], v[194:197], v[112:115]
	v_mfma_f32_16x16x32_bf16 v[108:111], v[128:131], v[202:205], v[108:111]
	v_mfma_f32_16x16x32_bf16 v[104:107], v[136:139], v[202:205], v[104:107]
	v_mfma_f32_16x16x32_bf16 v[100:103], v[128:131], v[210:213], v[100:103]
	v_mfma_f32_16x16x32_bf16 v[96:99], v[136:139], v[210:213], v[96:99]
	v_mfma_f32_16x16x32_bf16 v[124:127], v[132:135], v[190:193], v[124:127]
	v_mfma_f32_16x16x32_bf16 v[120:123], v[140:143], v[190:193], v[120:123]
	v_mfma_f32_16x16x32_bf16 v[116:119], v[132:135], v[198:201], v[116:119]
	v_mfma_f32_16x16x32_bf16 v[112:115], v[140:143], v[198:201], v[112:115]
	v_mfma_f32_16x16x32_bf16 v[108:111], v[132:135], v[206:209], v[108:111]
	v_mfma_f32_16x16x32_bf16 v[104:107], v[140:143], v[206:209], v[104:107]
	v_mfma_f32_16x16x32_bf16 v[100:103], v[132:135], v[214:217], v[100:103]
	v_mfma_f32_16x16x32_bf16 v[96:99], v[140:143], v[214:217], v[96:99]
	s_setprio 0
	s_setprio 1
	v_mfma_f32_16x16x32_bf16 v[92:95], v[144:147], v[160:163], v[92:95]
	v_mfma_f32_16x16x32_bf16 v[88:91], v[152:155], v[160:163], v[88:91]
	v_mfma_f32_16x16x32_bf16 v[84:87], v[144:147], v[194:197], v[84:87]
	v_mfma_f32_16x16x32_bf16 v[80:83], v[152:155], v[194:197], v[80:83]
	v_mfma_f32_16x16x32_bf16 v[76:79], v[144:147], v[202:205], v[76:79]
	v_mfma_f32_16x16x32_bf16 v[72:75], v[152:155], v[202:205], v[72:75]
	v_mfma_f32_16x16x32_bf16 v[68:71], v[144:147], v[210:213], v[68:71]
	v_mfma_f32_16x16x32_bf16 v[64:67], v[152:155], v[210:213], v[64:67]
	v_mfma_f32_16x16x32_bf16 v[92:95], v[148:151], v[190:193], v[92:95]
	v_mfma_f32_16x16x32_bf16 v[88:91], v[156:159], v[190:193], v[88:91]
	v_mfma_f32_16x16x32_bf16 v[84:87], v[148:151], v[198:201], v[84:87]
	v_mfma_f32_16x16x32_bf16 v[80:83], v[156:159], v[198:201], v[80:83]
	v_mfma_f32_16x16x32_bf16 v[76:79], v[148:151], v[206:209], v[76:79]
	v_mfma_f32_16x16x32_bf16 v[72:75], v[156:159], v[206:209], v[72:75]
	v_mfma_f32_16x16x32_bf16 v[68:71], v[148:151], v[214:217], v[68:71]
	v_mfma_f32_16x16x32_bf16 v[64:67], v[156:159], v[214:217], v[64:67]
	s_setprio 0
	s_barrier
	s_add_i32 s59, s62, s42
	s_mov_b32 m0, s59
	s_nop 0
	global_load_lds_dwordx4 v166, s[34:35]
	s_add_i32 m0, s59, 0x2000
	s_add_u32 s72, s34, 0x20000
	s_addc_u32 s73, s35, 0
	s_add_i32 s59, s63, s42
	global_load_lds_dwordx4 v170, s[34:35]
	s_mov_b32 m0, s59
	s_nop 0
	global_load_lds_dwordx4 v166, s[72:73]
	s_add_i32 m0, s59, 0x2000
	s_nop 0
	global_load_lds_dwordx4 v170, s[72:73]
	s_mov_b32 m0, s43
	s_nop 0
	global_load_lds_dwordx4 v164, s[36:37]
	s_mov_b32 m0, s44
	s_nop 0
	global_load_lds_dwordx4 v168, s[36:37]
	ds_read_b128 v[160:163], v188 offset:16384
	ds_read_b128 v[190:193], v188 offset:17408
	ds_read_b128 v[194:197], v188 offset:18432
	ds_read_b128 v[198:201], v188 offset:19456
	ds_read_b128 v[202:205], v188 offset:20480
	ds_read_b128 v[206:209], v188 offset:21504
	ds_read_b128 v[210:213], v188 offset:22528
	ds_read_b128 v[214:217], v188 offset:23552
	s_waitcnt vmcnt(8)
	s_waitcnt lgkmcnt(0)
	s_barrier
	s_setprio 1
	s_waitcnt lgkmcnt(0)
	v_mfma_f32_16x16x32_bf16 v[60:63], v[128:131], v[160:163], v[60:63]
	v_mfma_f32_16x16x32_bf16 v[56:59], v[136:139], v[160:163], v[56:59]
	v_mfma_f32_16x16x32_bf16 v[52:55], v[128:131], v[194:197], v[52:55]
	v_mfma_f32_16x16x32_bf16 v[48:51], v[136:139], v[194:197], v[48:51]
	v_mfma_f32_16x16x32_bf16 v[44:47], v[128:131], v[202:205], v[44:47]
	v_mfma_f32_16x16x32_bf16 v[40:43], v[136:139], v[202:205], v[40:43]
	v_mfma_f32_16x16x32_bf16 v[36:39], v[128:131], v[210:213], v[36:39]
	v_mfma_f32_16x16x32_bf16 v[32:35], v[136:139], v[210:213], v[32:35]
	v_mfma_f32_16x16x32_bf16 v[60:63], v[132:135], v[190:193], v[60:63]
	v_mfma_f32_16x16x32_bf16 v[56:59], v[140:143], v[190:193], v[56:59]
	v_mfma_f32_16x16x32_bf16 v[52:55], v[132:135], v[198:201], v[52:55]
	v_mfma_f32_16x16x32_bf16 v[48:51], v[140:143], v[198:201], v[48:51]
	v_mfma_f32_16x16x32_bf16 v[44:47], v[132:135], v[206:209], v[44:47]
	v_mfma_f32_16x16x32_bf16 v[40:43], v[140:143], v[206:209], v[40:43]
	v_mfma_f32_16x16x32_bf16 v[36:39], v[132:135], v[214:217], v[36:39]
	v_mfma_f32_16x16x32_bf16 v[32:35], v[140:143], v[214:217], v[32:35]
	s_setprio 0
	s_setprio 1
	v_mfma_f32_16x16x32_bf16 v[28:31], v[144:147], v[160:163], v[28:31]
	v_mfma_f32_16x16x32_bf16 v[24:27], v[152:155], v[160:163], v[24:27]
	v_mfma_f32_16x16x32_bf16 v[20:23], v[144:147], v[194:197], v[20:23]
	v_mfma_f32_16x16x32_bf16 v[16:19], v[152:155], v[194:197], v[16:19]
	v_mfma_f32_16x16x32_bf16 v[12:15], v[144:147], v[202:205], v[12:15]
	v_mfma_f32_16x16x32_bf16 v[8:11], v[152:155], v[202:205], v[8:11]
	v_mfma_f32_16x16x32_bf16 v[4:7], v[144:147], v[210:213], v[4:7]
	v_mfma_f32_16x16x32_bf16 v[0:3], v[152:155], v[210:213], v[0:3]
	v_mfma_f32_16x16x32_bf16 v[28:31], v[148:151], v[190:193], v[28:31]
	v_mfma_f32_16x16x32_bf16 v[24:27], v[156:159], v[190:193], v[24:27]
	v_mfma_f32_16x16x32_bf16 v[20:23], v[148:151], v[198:201], v[20:23]
	v_mfma_f32_16x16x32_bf16 v[16:19], v[156:159], v[198:201], v[16:19]
	v_mfma_f32_16x16x32_bf16 v[12:15], v[148:151], v[206:209], v[12:15]
	v_mfma_f32_16x16x32_bf16 v[8:11], v[156:159], v[206:209], v[8:11]
	v_mfma_f32_16x16x32_bf16 v[4:7], v[148:151], v[214:217], v[4:7]
	v_mfma_f32_16x16x32_bf16 v[0:3], v[156:159], v[214:217], v[0:3]
	s_setprio 0
	s_barrier
; #define PG8_STAGE(bufoff, gbase, voff) do { _Pragma("unroll") for (int _i = 0; _i < 2; ++_i) \
;         __builtin_amdgcn_global_load_lds((const unsigned*)((const char*)(gbase) + (voff)[_i]), (LAS unsigned*)(lds + (bufoff) + ldsw + _i * 8192), 16, 0, 0); } while (0)
; #define PG8_LDA(dst, b, h) do { _Pragma("unroll") for (int m = 0; m < 4; ++m) _Pragma("unroll") for (int k = 0; k < 2; ++k) dst[m][k] = *(const LAS bf16x8*)(lds + PG8_SA(b, h) + aoff + m * 2048 + k * 1024); } while (0)
; #define PG8_LDB(dst, b, h) do { _Pragma("unroll") for (int n = 0; n < 2; ++n) _Pragma("unroll") for (int k = 0; k < 2; ++k) dst[n][k] = *(const LAS bf16x8*)(lds + PG8_SB(b, h) + boff + n * 2048 + k * 1024); } while (0)
; #define PG8_MMA(ai, bj, At, Bt) do { __builtin_amdgcn_s_setprio(1); _Pragma("unroll") for (int m = 0; m < 4; ++m) _Pragma("unroll") for (int n = 0; n < 2; ++n) _Pragma("unroll") for (int k = 0; k < 2; ++k) \
;         acc[ai][bj][m][n] = __builtin_amdgcn_mfma_f32_16x16x32_bf16(Bt[n][k], At[m][k], acc[ai][bj][m][n], 0, 0, 0); __builtin_amdgcn_s_setprio(0); } while (0)
; #define PG8_WAIT_V(n) asm volatile("s_waitcnt vmcnt(" #n ")" ::: "memory")
; #define PG8_WAIT_L(n) asm volatile("s_waitcnt lgkmcnt(" #n ")" ::: "memory")
; #define PG8_BAR __builtin_amdgcn_s_barrier()
; #define PG8_SCHED __builtin_amdgcn_sched_barrier(0)
; template <class Epi, class Sched, bool ALIGN_EPI, bool SP2>
; __device__ __forceinline__ void gemm_phase(LAS unsigned char* lds, const Gemm g, const Sched& S, const Epi& E) {
;     ...
;             PG8_LDB(B0, 1, 0); PG8_LDB(B1, 1, 1); PG8_SCHED; PG8_LDA(At, 1, 0); PG8_STAGE(PG8_SA(0, 1), a2 + hstep, voffA);
;             PG8_WAIT_V(8); PG8_WAIT_L(0); PG8_BAR; PG8_MMA(0, 0, At, B0); PG8_MMA(0, 1, At, B1); PG8_BAR; PG8_SCHED;
;             PG8_LDA(At, 1, 1); PG8_STAGE(PG8_SB(1, 0), b3, voffB); PG8_STAGE(PG8_SB(1, 1), b3 + hstep, voffB); PG8_STAGE(PG8_SA(1, 0), a3, voffA);
;             PG8_WAIT_V(8); PG8_WAIT_L(0); PG8_BAR; PG8_MMA(1, 0, At, B0); PG8_MMA(1, 1, At, B1); PG8_BAR; PG8_SCHED;
	s_add_i32 s59, 0, 0x18000
	s_add_i32 s71, 0, 0x1c000
	v_add_u32_e32 v140, s59, v187
	v_add_u32_e32 v156, s71, v187
	ds_read_b128 v[128:131], v140
	ds_read_b128 v[132:135], v140 offset:1024
	ds_read_b128 v[136:139], v140 offset:2048
	ds_read_b128 v[140:143], v140 offset:3072
	ds_read_b128 v[144:147], v156
	ds_read_b128 v[148:151], v156 offset:1024
	ds_read_b128 v[152:155], v156 offset:2048
	ds_read_b128 v[156:159], v156 offset:3072
	s_add_u32 s36, s36, 0x20000
	s_addc_u32 s37, s37, 0
	s_mov_b32 m0, s45
	ds_read_b128 v[160:163], v188 offset:32768
	ds_read_b128 v[190:193], v188 offset:33792
	ds_read_b128 v[194:197], v188 offset:34816
	ds_read_b128 v[198:201], v188 offset:35840
	ds_read_b128 v[202:205], v188 offset:36864
	ds_read_b128 v[206:209], v188 offset:37888
	ds_read_b128 v[210:213], v188 offset:38912
	ds_read_b128 v[214:217], v188 offset:39936
	global_load_lds_dwordx4 v164, s[36:37]
	s_mov_b32 m0, s46
	s_nop 0
	global_load_lds_dwordx4 v168, s[36:37]
	s_waitcnt vmcnt(8)
	s_waitcnt lgkmcnt(0)
	s_barrier
	s_setprio 1
	s_waitcnt lgkmcnt(0)
	v_mfma_f32_16x16x32_bf16 v[124:127], v[128:131], v[160:163], v[124:127]
	v_mfma_f32_16x16x32_bf16 v[120:123], v[136:139], v[160:163], v[120:123]
	v_mfma_f32_16x16x32_bf16 v[116:119], v[128:131], v[194:197], v[116:119]
	v_mfma_f32_16x16x32_bf16 v[112:115], v[136:139], v[194:197], v[112:115]
	v_mfma_f32_16x16x32_bf16 v[108:111], v[128:131], v[202:205], v[108:111]
	v_mfma_f32_16x16x32_bf16 v[104:107], v[136:139], v[202:205], v[104:107]
	v_mfma_f32_16x16x32_bf16 v[100:103], v[128:131], v[210:213], v[100:103]
	v_mfma_f32_16x16x32_bf16 v[96:99], v[136:139], v[210:213], v[96:99]
	v_mfma_f32_16x16x32_bf16 v[124:127], v[132:135], v[190:193], v[124:127]
	v_mfma_f32_16x16x32_bf16 v[120:123], v[140:143], v[190:193], v[120:123]
	v_mfma_f32_16x16x32_bf16 v[116:119], v[132:135], v[198:201], v[116:119]
	v_mfma_f32_16x16x32_bf16 v[112:115], v[140:143], v[198:201], v[112:115]
	v_mfma_f32_16x16x32_bf16 v[108:111], v[132:135], v[206:209], v[108:111]
	v_mfma_f32_16x16x32_bf16 v[104:107], v[140:143], v[206:209], v[104:107]
	v_mfma_f32_16x16x32_bf16 v[100:103], v[132:135], v[214:217], v[100:103]
	v_mfma_f32_16x16x32_bf16 v[96:99], v[140:143], v[214:217], v[96:99]
	s_setprio 0
	s_setprio 1
	v_mfma_f32_16x16x32_bf16 v[92:95], v[144:147], v[160:163], v[92:95]
	v_mfma_f32_16x16x32_bf16 v[88:91], v[152:155], v[160:163], v[88:91]
	v_mfma_f32_16x16x32_bf16 v[84:87], v[144:147], v[194:197], v[84:87]
	v_mfma_f32_16x16x32_bf16 v[80:83], v[152:155], v[194:197], v[80:83]
	v_mfma_f32_16x16x32_bf16 v[76:79], v[144:147], v[202:205], v[76:79]
	v_mfma_f32_16x16x32_bf16 v[72:75], v[152:155], v[202:205], v[72:75]
	v_mfma_f32_16x16x32_bf16 v[68:71], v[144:147], v[210:213], v[68:71]
	v_mfma_f32_16x16x32_bf16 v[64:67], v[152:155], v[210:213], v[64:67]
	v_mfma_f32_16x16x32_bf16 v[92:95], v[148:151], v[190:193], v[92:95]
	v_mfma_f32_16x16x32_bf16 v[88:91], v[156:159], v[190:193], v[88:91]
	v_mfma_f32_16x16x32_bf16 v[84:87], v[148:151], v[198:201], v[84:87]
	v_mfma_f32_16x16x32_bf16 v[80:83], v[156:159], v[198:201], v[80:83]
	v_mfma_f32_16x16x32_bf16 v[76:79], v[148:151], v[206:209], v[76:79]
	v_mfma_f32_16x16x32_bf16 v[72:75], v[156:159], v[206:209], v[72:75]
	v_mfma_f32_16x16x32_bf16 v[68:71], v[148:151], v[214:217], v[68:71]
	v_mfma_f32_16x16x32_bf16 v[64:67], v[156:159], v[214:217], v[64:67]
	s_setprio 0
	s_barrier
	s_add_u32 s100, s36, 0xfffe0080
	s_addc_u32 s101, s37, -1
	s_add_u32 s98, s34, 0x80
	s_addc_u32 s99, s35, 0
	s_add_i32 s36, s59, s42
	s_mov_b32 m0, s36
	s_nop 0
	global_load_lds_dwordx4 v166, s[98:99]
	s_add_i32 m0, s36, 0x2000
	s_add_u32 s34, s34, 0x20080
	s_addc_u32 s35, s35, 0
	s_add_i32 s36, s71, s42
	global_load_lds_dwordx4 v170, s[98:99]
	s_mov_b32 m0, s36
	s_nop 0
	global_load_lds_dwordx4 v166, s[34:35]
	s_add_i32 m0, s36, 0x2000
	s_nop 0
	global_load_lds_dwordx4 v170, s[34:35]
	s_mov_b32 m0, s54
	s_nop 0
	global_load_lds_dwordx4 v164, s[100:101]
	s_mov_b32 m0, s55
	s_nop 0
	global_load_lds_dwordx4 v168, s[100:101]
	ds_read_b128 v[160:163], v188 offset:49152
	ds_read_b128 v[190:193], v188 offset:50176
	ds_read_b128 v[194:197], v188 offset:51200
	ds_read_b128 v[198:201], v188 offset:52224
	ds_read_b128 v[202:205], v188 offset:53248
	ds_read_b128 v[206:209], v188 offset:54272
	ds_read_b128 v[210:213], v188 offset:55296
	ds_read_b128 v[214:217], v188 offset:56320
	s_waitcnt vmcnt(8)
	s_waitcnt lgkmcnt(0)
	s_barrier
	s_setprio 1
	s_waitcnt lgkmcnt(0)
	v_mfma_f32_16x16x32_bf16 v[60:63], v[128:131], v[160:163], v[60:63]
	v_mfma_f32_16x16x32_bf16 v[56:59], v[136:139], v[160:163], v[56:59]
	v_mfma_f32_16x16x32_bf16 v[52:55], v[128:131], v[194:197], v[52:55]
	v_mfma_f32_16x16x32_bf16 v[48:51], v[136:139], v[194:197], v[48:51]
	v_mfma_f32_16x16x32_bf16 v[44:47], v[128:131], v[202:205], v[44:47]
	v_mfma_f32_16x16x32_bf16 v[40:43], v[136:139], v[202:205], v[40:43]
	v_mfma_f32_16x16x32_bf16 v[36:39], v[128:131], v[210:213], v[36:39]
	v_mfma_f32_16x16x32_bf16 v[32:35], v[136:139], v[210:213], v[32:35]
	v_mfma_f32_16x16x32_bf16 v[60:63], v[132:135], v[190:193], v[60:63]
	v_mfma_f32_16x16x32_bf16 v[56:59], v[140:143], v[190:193], v[56:59]
	v_mfma_f32_16x16x32_bf16 v[52:55], v[132:135], v[198:201], v[52:55]
	v_mfma_f32_16x16x32_bf16 v[48:51], v[140:143], v[198:201], v[48:51]
	v_mfma_f32_16x16x32_bf16 v[44:47], v[132:135], v[206:209], v[44:47]
	v_mfma_f32_16x16x32_bf16 v[40:43], v[140:143], v[206:209], v[40:43]
	v_mfma_f32_16x16x32_bf16 v[36:39], v[132:135], v[214:217], v[36:39]
	v_mfma_f32_16x16x32_bf16 v[32:35], v[140:143], v[214:217], v[32:35]
	s_setprio 0
	s_setprio 1
	v_mfma_f32_16x16x32_bf16 v[28:31], v[144:147], v[160:163], v[28:31]
	v_mfma_f32_16x16x32_bf16 v[24:27], v[152:155], v[160:163], v[24:27]
	v_mfma_f32_16x16x32_bf16 v[20:23], v[144:147], v[194:197], v[20:23]
	v_mfma_f32_16x16x32_bf16 v[16:19], v[152:155], v[194:197], v[16:19]
	v_mfma_f32_16x16x32_bf16 v[12:15], v[144:147], v[202:205], v[12:15]
	v_mfma_f32_16x16x32_bf16 v[8:11], v[152:155], v[202:205], v[8:11]
	v_mfma_f32_16x16x32_bf16 v[4:7], v[144:147], v[210:213], v[4:7]
	v_mfma_f32_16x16x32_bf16 v[0:3], v[152:155], v[210:213], v[0:3]
	v_mfma_f32_16x16x32_bf16 v[28:31], v[148:151], v[190:193], v[28:31]
	v_mfma_f32_16x16x32_bf16 v[24:27], v[156:159], v[190:193], v[24:27]
	v_mfma_f32_16x16x32_bf16 v[20:23], v[148:151], v[198:201], v[20:23]
	v_mfma_f32_16x16x32_bf16 v[16:19], v[156:159], v[198:201], v[16:19]
	v_mfma_f32_16x16x32_bf16 v[12:15], v[148:151], v[206:209], v[12:15]
	v_mfma_f32_16x16x32_bf16 v[8:11], v[156:159], v[206:209], v[8:11]
	v_mfma_f32_16x16x32_bf16 v[4:7], v[148:151], v[214:217], v[4:7]
	v_mfma_f32_16x16x32_bf16 v[0:3], v[156:159], v[214:217], v[0:3]
	s_setprio 0
	s_barrier
	s_add_i32 s58, s58, 2
	s_add_u32 s28, s28, 0x100
	s_addc_u32 s29, s29, 0
	s_add_u32 s56, s56, 0x100
	s_addc_u32 s57, s57, 0
	s_cmp_gt_u32 s58, 5
	s_cbranch_scc0 .LBB0_468
	s_and_b64 vcc, exec, s[18:19]
	s_cbranch_vccz .LBB0_471
	s_barrier

; #define PG8_STAGE(bufoff, gbase, voff) do { _Pragma("unroll") for (int _i = 0; _i < 2; ++_i) \
;         __builtin_amdgcn_global_load_lds((const unsigned*)((const char*)(gbase) + (voff)[_i]), (LAS unsigned*)(lds + (bufoff) + ldsw + _i * 8192), 16, 0, 0); } while (0)
; #define PG8_LDA(dst, b, h) do { _Pragma("unroll") for (int m = 0; m < 4; ++m) _Pragma("unroll") for (int k = 0; k < 2; ++k) dst[m][k] = *(const LAS bf16x8*)(lds + PG8_SA(b, h) + aoff + m * 2048 + k * 1024); } while (0)
; #define PG8_LDB(dst, b, h) do { _Pragma("unroll") for (int n = 0; n < 2; ++n) _Pragma("unroll") for (int k = 0; k < 2; ++k) dst[n][k] = *(const LAS bf16x8*)(lds + PG8_SB(b, h) + boff + n * 2048 + k * 1024); } while (0)
; #define PG8_MMA(ai, bj, At, Bt) do { __builtin_amdgcn_s_setprio(1); _Pragma("unroll") for (int m = 0; m < 4; ++m) _Pragma("unroll") for (int n = 0; n < 2; ++n) _Pragma("unroll") for (int k = 0; k < 2; ++k) \
;         acc[ai][bj][m][n] = __builtin_amdgcn_mfma_f32_16x16x32_bf16(Bt[n][k], At[m][k], acc[ai][bj][m][n], 0, 0, 0); __builtin_amdgcn_s_setprio(0); } while (0)
; #define PG8_WAIT_V(n) asm volatile("s_waitcnt vmcnt(" #n ")" ::: "memory")
; #define PG8_WAIT_L(n) asm volatile("s_waitcnt lgkmcnt(" #n ")" ::: "memory")
; #define PG8_BAR __builtin_amdgcn_s_barrier()
; #define PG8_SCHED __builtin_amdgcn_sched_barrier(0)
; template <class Epi, class Sched, bool ALIGN_EPI, bool SP2>
; __device__ __forceinline__ void gemm_phase(LAS unsigned char* lds, const Gemm g, const Sched& S, const Epi& E) {
;     ...
;             PG8_LDB(B0, 0, 0); PG8_LDB(B1, 0, 1); PG8_SCHED; PG8_LDA(At, 0, 0); PG8_STAGE(PG8_SA(1, 1), a1 + hstep, voffA);
;             PG8_WAIT_V(8); PG8_WAIT_L(0); PG8_BAR; PG8_MMA(0, 0, At, B0); PG8_MMA(0, 1, At, B1); PG8_BAR; PG8_SCHED;
;             PG8_LDA(At, 0, 1); PG8_STAGE(PG8_SB(0, 0), b2, voffB); PG8_STAGE(PG8_SB(0, 1), b2 + hstep, voffB); PG8_STAGE(PG8_SA(0, 0), a2, voffA);
;             PG8_WAIT_V(8); PG8_WAIT_L(0); PG8_BAR; PG8_MMA(1, 0, At, B0); PG8_MMA(1, 1, At, B1); PG8_BAR; PG8_SCHED;
.LBB0_553:
	ds_read_b128 v[128:131], v167
	ds_read_b128 v[132:135], v167 offset:1024
	ds_read_b128 v[136:139], v167 offset:2048
	ds_read_b128 v[140:143], v167 offset:3072
	ds_read_b128 v[160:163], v168
	ds_read_b128 v[170:173], v168 offset:1024
	ds_read_b128 v[176:179], v168 offset:2048
	ds_read_b128 v[180:183], v168 offset:3072
	s_add_u32 s36, s34, 0xfffc0080
	s_addc_u32 s37, s35, -1
	s_cmp_eq_u32 s59, 12
	s_cselect_b32 s39, s23, s37
	s_cselect_b32 s38, s51, s36
	s_cselect_b32 s37, s25, s58
	s_cselect_b32 s36, s56, s57
	s_add_i32 m0, s31, 0xc000
	ds_read_b128 v[184:187], v169
	ds_read_b128 v[188:191], v169 offset:1024
	ds_read_b128 v[192:195], v169 offset:2048
	ds_read_b128 v[196:199], v169 offset:3072
	ds_read_b128 v[200:203], v169 offset:4096
	ds_read_b128 v[204:207], v169 offset:5120
	ds_read_b128 v[208:211], v169 offset:6144
	ds_read_b128 v[212:215], v169 offset:7168
	global_load_lds_dwordx4 v152, s[34:35]
	s_add_i32 m0, s31, 0xe000
	s_nop 0
	global_load_lds_dwordx4 v154, s[34:35]
	s_waitcnt vmcnt(8)
	s_waitcnt lgkmcnt(0)
	s_barrier
	s_setprio 1
	s_waitcnt lgkmcnt(0)
	v_mfma_f32_16x16x32_bf16 v[124:127], v[128:131], v[184:187], v[124:127]
	v_mfma_f32_16x16x32_bf16 v[120:123], v[136:139], v[184:187], v[120:123]
	v_mfma_f32_16x16x32_bf16 v[108:111], v[128:131], v[192:195], v[108:111]
	v_mfma_f32_16x16x32_bf16 v[104:107], v[136:139], v[192:195], v[104:107]
	v_mfma_f32_16x16x32_bf16 v[92:95], v[128:131], v[200:203], v[92:95]
	v_mfma_f32_16x16x32_bf16 v[88:91], v[136:139], v[200:203], v[88:91]
	v_mfma_f32_16x16x32_bf16 v[76:79], v[128:131], v[208:211], v[76:79]
	v_mfma_f32_16x16x32_bf16 v[72:75], v[136:139], v[208:211], v[72:75]
	v_mfma_f32_16x16x32_bf16 v[124:127], v[132:135], v[188:191], v[124:127]
	v_mfma_f32_16x16x32_bf16 v[120:123], v[140:143], v[188:191], v[120:123]
	v_mfma_f32_16x16x32_bf16 v[108:111], v[132:135], v[196:199], v[108:111]
	v_mfma_f32_16x16x32_bf16 v[104:107], v[140:143], v[196:199], v[104:107]
	v_mfma_f32_16x16x32_bf16 v[92:95], v[132:135], v[204:207], v[92:95]
	v_mfma_f32_16x16x32_bf16 v[88:91], v[140:143], v[204:207], v[88:91]
	v_mfma_f32_16x16x32_bf16 v[76:79], v[132:135], v[212:215], v[76:79]
	v_mfma_f32_16x16x32_bf16 v[72:75], v[140:143], v[212:215], v[72:75]
	s_setprio 0
	s_setprio 1
	v_mfma_f32_16x16x32_bf16 v[116:119], v[160:163], v[184:187], v[116:119]
	v_mfma_f32_16x16x32_bf16 v[112:115], v[176:179], v[184:187], v[112:115]
	v_mfma_f32_16x16x32_bf16 v[100:103], v[160:163], v[192:195], v[100:103]
	v_mfma_f32_16x16x32_bf16 v[96:99], v[176:179], v[192:195], v[96:99]
	v_mfma_f32_16x16x32_bf16 v[84:87], v[160:163], v[200:203], v[84:87]
	v_mfma_f32_16x16x32_bf16 v[80:83], v[176:179], v[200:203], v[80:83]
	v_mfma_f32_16x16x32_bf16 v[68:71], v[160:163], v[208:211], v[68:71]
	v_mfma_f32_16x16x32_bf16 v[64:67], v[176:179], v[208:211], v[64:67]
	v_mfma_f32_16x16x32_bf16 v[116:119], v[170:173], v[188:191], v[116:119]
	v_mfma_f32_16x16x32_bf16 v[112:115], v[180:183], v[188:191], v[112:115]
	v_mfma_f32_16x16x32_bf16 v[100:103], v[170:173], v[196:199], v[100:103]
	v_mfma_f32_16x16x32_bf16 v[96:99], v[180:183], v[196:199], v[96:99]
	v_mfma_f32_16x16x32_bf16 v[84:87], v[170:173], v[204:207], v[84:87]
	v_mfma_f32_16x16x32_bf16 v[80:83], v[180:183], v[204:207], v[80:83]
	v_mfma_f32_16x16x32_bf16 v[68:71], v[170:173], v[212:215], v[68:71]
	v_mfma_f32_16x16x32_bf16 v[64:67], v[180:183], v[212:215], v[64:67]
	s_setprio 0
	s_barrier
	s_add_i32 s64, s62, s73
	s_mov_b32 m0, s64
	s_nop 0
	global_load_lds_dwordx4 v146, s[36:37]
	s_add_i32 m0, s64, 0x2000
	s_add_u32 s64, s36, 0x40000
	s_addc_u32 s65, s37, 0
	s_add_i32 s66, s63, s73
	global_load_lds_dwordx4 v150, s[36:37]
	s_mov_b32 m0, s66
	s_nop 0
	global_load_lds_dwordx4 v146, s[64:65]
	s_add_i32 m0, s66, 0x2000
	s_nop 0
	global_load_lds_dwordx4 v150, s[64:65]
	s_mov_b32 m0, s31
	s_nop 0
	global_load_lds_dwordx4 v144, s[38:39]
	s_mov_b32 m0, s68
	s_nop 0
	global_load_lds_dwordx4 v148, s[38:39]
	ds_read_b128 v[184:187], v169 offset:16384
	ds_read_b128 v[188:191], v169 offset:17408
	ds_read_b128 v[192:195], v169 offset:18432
	ds_read_b128 v[196:199], v169 offset:19456
	ds_read_b128 v[200:203], v169 offset:20480
	ds_read_b128 v[204:207], v169 offset:21504
	ds_read_b128 v[208:211], v169 offset:22528
	ds_read_b128 v[212:215], v169 offset:23552
	s_waitcnt vmcnt(8)
	s_waitcnt lgkmcnt(0)
	s_barrier
	s_setprio 1
	s_waitcnt lgkmcnt(0)
	v_mfma_f32_16x16x32_bf16 v[60:63], v[128:131], v[184:187], v[60:63]
	v_mfma_f32_16x16x32_bf16 v[56:59], v[136:139], v[184:187], v[56:59]
	v_mfma_f32_16x16x32_bf16 v[44:47], v[128:131], v[192:195], v[44:47]
	v_mfma_f32_16x16x32_bf16 v[40:43], v[136:139], v[192:195], v[40:43]
	v_mfma_f32_16x16x32_bf16 v[28:31], v[128:131], v[200:203], v[28:31]
	v_mfma_f32_16x16x32_bf16 v[24:27], v[136:139], v[200:203], v[24:27]
	v_mfma_f32_16x16x32_bf16 v[12:15], v[128:131], v[208:211], v[12:15]
	v_mfma_f32_16x16x32_bf16 v[8:11], v[136:139], v[208:211], v[8:11]
	v_mfma_f32_16x16x32_bf16 v[60:63], v[132:135], v[188:191], v[60:63]
	v_mfma_f32_16x16x32_bf16 v[56:59], v[140:143], v[188:191], v[56:59]
	v_mfma_f32_16x16x32_bf16 v[44:47], v[132:135], v[196:199], v[44:47]
	v_mfma_f32_16x16x32_bf16 v[40:43], v[140:143], v[196:199], v[40:43]
	v_mfma_f32_16x16x32_bf16 v[28:31], v[132:135], v[204:207], v[28:31]
	v_mfma_f32_16x16x32_bf16 v[24:27], v[140:143], v[204:207], v[24:27]
	v_mfma_f32_16x16x32_bf16 v[12:15], v[132:135], v[212:215], v[12:15]
	v_mfma_f32_16x16x32_bf16 v[8:11], v[140:143], v[212:215], v[8:11]
	s_setprio 0
	s_setprio 1
	v_mfma_f32_16x16x32_bf16 v[52:55], v[160:163], v[184:187], v[52:55]
	v_mfma_f32_16x16x32_bf16 v[48:51], v[176:179], v[184:187], v[48:51]
	v_mfma_f32_16x16x32_bf16 v[36:39], v[160:163], v[192:195], v[36:39]
	v_mfma_f32_16x16x32_bf16 v[32:35], v[176:179], v[192:195], v[32:35]
	v_mfma_f32_16x16x32_bf16 v[20:23], v[160:163], v[200:203], v[20:23]
	v_mfma_f32_16x16x32_bf16 v[16:19], v[176:179], v[200:203], v[16:19]
	v_mfma_f32_16x16x32_bf16 v[4:7], v[160:163], v[208:211], v[4:7]
	v_mfma_f32_16x16x32_bf16 v[0:3], v[176:179], v[208:211], v[0:3]
	v_mfma_f32_16x16x32_bf16 v[52:55], v[170:173], v[188:191], v[52:55]
	v_mfma_f32_16x16x32_bf16 v[48:51], v[180:183], v[188:191], v[48:51]
	v_mfma_f32_16x16x32_bf16 v[36:39], v[170:173], v[196:199], v[36:39]
	v_mfma_f32_16x16x32_bf16 v[32:35], v[180:183], v[196:199], v[32:35]
	v_mfma_f32_16x16x32_bf16 v[20:23], v[170:173], v[204:207], v[20:23]
	v_mfma_f32_16x16x32_bf16 v[16:19], v[180:183], v[204:207], v[16:19]
	v_mfma_f32_16x16x32_bf16 v[4:7], v[170:173], v[212:215], v[4:7]
	v_mfma_f32_16x16x32_bf16 v[0:3], v[180:183], v[212:215], v[0:3]
	s_setprio 0
	s_barrier
; #define PG8_STAGE(bufoff, gbase, voff) do { _Pragma("unroll") for (int _i = 0; _i < 2; ++_i) \
;         __builtin_amdgcn_global_load_lds((const unsigned*)((const char*)(gbase) + (voff)[_i]), (LAS unsigned*)(lds + (bufoff) + ldsw + _i * 8192), 16, 0, 0); } while (0)
; #define PG8_LDA(dst, b, h) do { _Pragma("unroll") for (int m = 0; m < 4; ++m) _Pragma("unroll") for (int k = 0; k < 2; ++k) dst[m][k] = *(const LAS bf16x8*)(lds + PG8_SA(b, h) + aoff + m * 2048 + k * 1024); } while (0)
; #define PG8_LDB(dst, b, h) do { _Pragma("unroll") for (int n = 0; n < 2; ++n) _Pragma("unroll") for (int k = 0; k < 2; ++k) dst[n][k] = *(const LAS bf16x8*)(lds + PG8_SB(b, h) + boff + n * 2048 + k * 1024); } while (0)
; #define PG8_MMA(ai, bj, At, Bt) do { __builtin_amdgcn_s_setprio(1); _Pragma("unroll") for (int m = 0; m < 4; ++m) _Pragma("unroll") for (int n = 0; n < 2; ++n) _Pragma("unroll") for (int k = 0; k < 2; ++k) \
;         acc[ai][bj][m][n] = __builtin_amdgcn_mfma_f32_16x16x32_bf16(Bt[n][k], At[m][k], acc[ai][bj][m][n], 0, 0, 0); __builtin_amdgcn_s_setprio(0); } while (0)
; #define PG8_WAIT_V(n) asm volatile("s_waitcnt vmcnt(" #n ")" ::: "memory")
; #define PG8_WAIT_L(n) asm volatile("s_waitcnt lgkmcnt(" #n ")" ::: "memory")
; #define PG8_BAR __builtin_amdgcn_s_barrier()
; #define PG8_SCHED __builtin_amdgcn_sched_barrier(0)
; template <class Epi, class Sched, bool ALIGN_EPI, bool SP2>
; __device__ __forceinline__ void gemm_phase(LAS unsigned char* lds, const Gemm g, const Sched& S, const Epi& E) {
;     ...
;             PG8_LDB(B0, 1, 0); PG8_LDB(B1, 1, 1); PG8_SCHED; PG8_LDA(At, 1, 0); PG8_STAGE(PG8_SA(0, 1), a2 + hstep, voffA);
;             PG8_WAIT_V(8); PG8_WAIT_L(0); PG8_BAR; PG8_MMA(0, 0, At, B0); PG8_MMA(0, 1, At, B1); PG8_BAR; PG8_SCHED;
;             PG8_LDA(At, 1, 1); PG8_STAGE(PG8_SB(1, 0), b3, voffB); PG8_STAGE(PG8_SB(1, 1), b3 + hstep, voffB); PG8_STAGE(PG8_SA(1, 0), a3, voffA);
;             PG8_WAIT_V(8); PG8_WAIT_L(0); PG8_BAR; PG8_MMA(1, 0, At, B0); PG8_MMA(1, 1, At, B1); PG8_BAR; PG8_SCHED;
	s_add_i32 s64, 0, 0x18000
	s_add_i32 s65, 0, 0x1c000
	v_add_u32_e32 v140, s64, v165
	v_add_u32_e32 v174, s65, v165
	ds_read_b128 v[128:131], v140
	ds_read_b128 v[132:135], v140 offset:1024
	ds_read_b128 v[136:139], v140 offset:2048
	ds_read_b128 v[140:143], v140 offset:3072
	ds_read_b128 v[160:163], v174
	ds_read_b128 v[170:173], v174 offset:1024
	ds_read_b128 v[176:179], v174 offset:2048
	ds_read_b128 v[180:183], v174 offset:3072
	s_add_u32 s38, s38, 0x40000
	s_addc_u32 s39, s39, 0
	s_mov_b32 m0, s69
	ds_read_b128 v[184:187], v169 offset:32768
	ds_read_b128 v[188:191], v169 offset:33792
	ds_read_b128 v[192:195], v169 offset:34816
	ds_read_b128 v[196:199], v169 offset:35840
	ds_read_b128 v[200:203], v169 offset:36864
	ds_read_b128 v[204:207], v169 offset:37888
	ds_read_b128 v[208:211], v169 offset:38912
	ds_read_b128 v[212:215], v169 offset:39936
	global_load_lds_dwordx4 v144, s[38:39]
	s_mov_b32 m0, s70
	s_nop 0
	global_load_lds_dwordx4 v148, s[38:39]
	s_waitcnt vmcnt(8)
	s_waitcnt lgkmcnt(0)
	s_barrier
	s_setprio 1
	s_waitcnt lgkmcnt(0)
	v_mfma_f32_16x16x32_bf16 v[124:127], v[128:131], v[184:187], v[124:127]
	v_mfma_f32_16x16x32_bf16 v[120:123], v[136:139], v[184:187], v[120:123]
	v_mfma_f32_16x16x32_bf16 v[108:111], v[128:131], v[192:195], v[108:111]
	v_mfma_f32_16x16x32_bf16 v[104:107], v[136:139], v[192:195], v[104:107]
	v_mfma_f32_16x16x32_bf16 v[92:95], v[128:131], v[200:203], v[92:95]
	v_mfma_f32_16x16x32_bf16 v[88:91], v[136:139], v[200:203], v[88:91]
	v_mfma_f32_16x16x32_bf16 v[76:79], v[128:131], v[208:211], v[76:79]
	v_mfma_f32_16x16x32_bf16 v[72:75], v[136:139], v[208:211], v[72:75]
	v_mfma_f32_16x16x32_bf16 v[124:127], v[132:135], v[188:191], v[124:127]
	v_mfma_f32_16x16x32_bf16 v[120:123], v[140:143], v[188:191], v[120:123]
	v_mfma_f32_16x16x32_bf16 v[108:111], v[132:135], v[196:199], v[108:111]
	v_mfma_f32_16x16x32_bf16 v[104:107], v[140:143], v[196:199], v[104:107]
	v_mfma_f32_16x16x32_bf16 v[92:95], v[132:135], v[204:207], v[92:95]
	v_mfma_f32_16x16x32_bf16 v[88:91], v[140:143], v[204:207], v[88:91]
	v_mfma_f32_16x16x32_bf16 v[76:79], v[132:135], v[212:215], v[76:79]
	v_mfma_f32_16x16x32_bf16 v[72:75], v[140:143], v[212:215], v[72:75]
	s_setprio 0
	s_setprio 1
	v_mfma_f32_16x16x32_bf16 v[116:119], v[160:163], v[184:187], v[116:119]
	v_mfma_f32_16x16x32_bf16 v[112:115], v[176:179], v[184:187], v[112:115]
	v_mfma_f32_16x16x32_bf16 v[100:103], v[160:163], v[192:195], v[100:103]
	v_mfma_f32_16x16x32_bf16 v[96:99], v[176:179], v[192:195], v[96:99]
	v_mfma_f32_16x16x32_bf16 v[84:87], v[160:163], v[200:203], v[84:87]
	v_mfma_f32_16x16x32_bf16 v[80:83], v[176:179], v[200:203], v[80:83]
	v_mfma_f32_16x16x32_bf16 v[68:71], v[160:163], v[208:211], v[68:71]
	v_mfma_f32_16x16x32_bf16 v[64:67], v[176:179], v[208:211], v[64:67]
	v_mfma_f32_16x16x32_bf16 v[116:119], v[170:173], v[188:191], v[116:119]
	v_mfma_f32_16x16x32_bf16 v[112:115], v[180:183], v[188:191], v[112:115]
	v_mfma_f32_16x16x32_bf16 v[100:103], v[170:173], v[196:199], v[100:103]
	v_mfma_f32_16x16x32_bf16 v[96:99], v[180:183], v[196:199], v[96:99]
	v_mfma_f32_16x16x32_bf16 v[84:87], v[170:173], v[204:207], v[84:87]
	v_mfma_f32_16x16x32_bf16 v[80:83], v[180:183], v[204:207], v[80:83]
	v_mfma_f32_16x16x32_bf16 v[68:71], v[170:173], v[212:215], v[68:71]
	v_mfma_f32_16x16x32_bf16 v[64:67], v[180:183], v[212:215], v[64:67]
	s_setprio 0
	s_barrier
	s_add_u32 s100, s38, 0xfffc0080
	s_addc_u32 s101, s39, -1
	s_add_u32 s98, s36, 0x80
	s_addc_u32 s99, s37, 0
	s_add_i32 s38, s64, s73
	s_mov_b32 m0, s38
	s_nop 0
	global_load_lds_dwordx4 v146, s[98:99]
	s_add_i32 m0, s38, 0x2000
	s_add_u32 s36, s36, 0x40080
	s_addc_u32 s37, s37, 0
	s_add_i32 s38, s65, s73
	global_load_lds_dwordx4 v150, s[98:99]
	s_mov_b32 m0, s38
	s_nop 0
	global_load_lds_dwordx4 v146, s[36:37]
	s_add_i32 m0, s38, 0x2000
	s_nop 0
	global_load_lds_dwordx4 v150, s[36:37]
	s_mov_b32 m0, s54
	s_nop 0
	global_load_lds_dwordx4 v144, s[100:101]
	s_mov_b32 m0, s55
	s_nop 0
	global_load_lds_dwordx4 v148, s[100:101]
	ds_read_b128 v[184:187], v169 offset:49152
	ds_read_b128 v[188:191], v169 offset:50176
	ds_read_b128 v[192:195], v169 offset:51200
	ds_read_b128 v[196:199], v169 offset:52224
	ds_read_b128 v[200:203], v169 offset:53248
	ds_read_b128 v[204:207], v169 offset:54272
	ds_read_b128 v[208:211], v169 offset:55296
	ds_read_b128 v[212:215], v169 offset:56320
	s_waitcnt vmcnt(8)
	s_waitcnt lgkmcnt(0)
	s_barrier
	s_setprio 1
	s_waitcnt lgkmcnt(0)
	v_mfma_f32_16x16x32_bf16 v[60:63], v[128:131], v[184:187], v[60:63]
	v_mfma_f32_16x16x32_bf16 v[56:59], v[136:139], v[184:187], v[56:59]
	v_mfma_f32_16x16x32_bf16 v[44:47], v[128:131], v[192:195], v[44:47]
	v_mfma_f32_16x16x32_bf16 v[40:43], v[136:139], v[192:195], v[40:43]
	v_mfma_f32_16x16x32_bf16 v[28:31], v[128:131], v[200:203], v[28:31]
	v_mfma_f32_16x16x32_bf16 v[24:27], v[136:139], v[200:203], v[24:27]
	v_mfma_f32_16x16x32_bf16 v[12:15], v[128:131], v[208:211], v[12:15]
	v_mfma_f32_16x16x32_bf16 v[8:11], v[136:139], v[208:211], v[8:11]
	v_mfma_f32_16x16x32_bf16 v[60:63], v[132:135], v[188:191], v[60:63]
	v_mfma_f32_16x16x32_bf16 v[56:59], v[140:143], v[188:191], v[56:59]
	v_mfma_f32_16x16x32_bf16 v[44:47], v[132:135], v[196:199], v[44:47]
	v_mfma_f32_16x16x32_bf16 v[40:43], v[140:143], v[196:199], v[40:43]
	v_mfma_f32_16x16x32_bf16 v[28:31], v[132:135], v[204:207], v[28:31]
	v_mfma_f32_16x16x32_bf16 v[24:27], v[140:143], v[204:207], v[24:27]
	v_mfma_f32_16x16x32_bf16 v[12:15], v[132:135], v[212:215], v[12:15]
	v_mfma_f32_16x16x32_bf16 v[8:11], v[140:143], v[212:215], v[8:11]
	s_setprio 0
	s_setprio 1
	v_mfma_f32_16x16x32_bf16 v[52:55], v[160:163], v[184:187], v[52:55]
	v_mfma_f32_16x16x32_bf16 v[48:51], v[176:179], v[184:187], v[48:51]
	v_mfma_f32_16x16x32_bf16 v[36:39], v[160:163], v[192:195], v[36:39]
	v_mfma_f32_16x16x32_bf16 v[32:35], v[176:179], v[192:195], v[32:35]
	v_mfma_f32_16x16x32_bf16 v[20:23], v[160:163], v[200:203], v[20:23]
	v_mfma_f32_16x16x32_bf16 v[16:19], v[176:179], v[200:203], v[16:19]
	v_mfma_f32_16x16x32_bf16 v[4:7], v[160:163], v[208:211], v[4:7]
	v_mfma_f32_16x16x32_bf16 v[0:3], v[176:179], v[208:211], v[0:3]
	v_mfma_f32_16x16x32_bf16 v[52:55], v[170:173], v[188:191], v[52:55]
	v_mfma_f32_16x16x32_bf16 v[48:51], v[180:183], v[188:191], v[48:51]
	v_mfma_f32_16x16x32_bf16 v[36:39], v[170:173], v[196:199], v[36:39]
	v_mfma_f32_16x16x32_bf16 v[32:35], v[180:183], v[196:199], v[32:35]
	v_mfma_f32_16x16x32_bf16 v[20:23], v[170:173], v[204:207], v[20:23]
	v_mfma_f32_16x16x32_bf16 v[16:19], v[180:183], v[204:207], v[16:19]
	v_mfma_f32_16x16x32_bf16 v[4:7], v[170:173], v[212:215], v[4:7]
	v_mfma_f32_16x16x32_bf16 v[0:3], v[180:183], v[212:215], v[0:3]
	s_setprio 0
	s_barrier
	s_add_i32 s59, s59, 2
	s_add_u32 s34, s34, 0x100
	s_addc_u32 s35, s35, 0
	s_add_u32 s57, s57, 0x100
	s_addc_u32 s58, s58, 0
	s_cmp_gt_u32 s59, 13
	s_cbranch_scc0 .LBB0_553
	s_and_b64 vcc, exec, s[12:13]
	s_cbranch_vccz .LBB0_556
	s_barrier

; #define PG8_STAGE(bufoff, gbase, voff) do { _Pragma("unroll") for (int _i = 0; _i < 2; ++_i) \
;         __builtin_amdgcn_global_load_lds((const unsigned*)((const char*)(gbase) + (voff)[_i]), (LAS unsigned*)(lds + (bufoff) + ldsw + _i * 8192), 16, 0, 0); } while (0)
; #define PG8_LDA(dst, b, h) do { _Pragma("unroll") for (int m = 0; m < 4; ++m) _Pragma("unroll") for (int k = 0; k < 2; ++k) dst[m][k] = *(const LAS bf16x8*)(lds + PG8_SA(b, h) + aoff + m * 2048 + k * 1024); } while (0)
; #define PG8_LDB(dst, b, h) do { _Pragma("unroll") for (int n = 0; n < 2; ++n) _Pragma("unroll") for (int k = 0; k < 2; ++k) dst[n][k] = *(const LAS bf16x8*)(lds + PG8_SB(b, h) + boff + n * 2048 + k * 1024); } while (0)
; #define PG8_MMA(ai, bj, At, Bt) do { __builtin_amdgcn_s_setprio(1); _Pragma("unroll") for (int m = 0; m < 4; ++m) _Pragma("unroll") for (int n = 0; n < 2; ++n) _Pragma("unroll") for (int k = 0; k < 2; ++k) \
;         acc[ai][bj][m][n] = __builtin_amdgcn_mfma_f32_16x16x32_bf16(Bt[n][k], At[m][k], acc[ai][bj][m][n], 0, 0, 0); __builtin_amdgcn_s_setprio(0); } while (0)
; #define PG8_WAIT_V(n) asm volatile("s_waitcnt vmcnt(" #n ")" ::: "memory")
; #define PG8_WAIT_L(n) asm volatile("s_waitcnt lgkmcnt(" #n ")" ::: "memory")
; #define PG8_BAR __builtin_amdgcn_s_barrier()
; #define PG8_SCHED __builtin_amdgcn_sched_barrier(0)
; template <class Epi, class Sched, bool ALIGN_EPI, bool SP2>
; __device__ __forceinline__ void gemm_phase(LAS unsigned char* lds, const Gemm g, const Sched& S, const Epi& E) {
;     ...
;             PG8_LDB(B0, 0, 0); PG8_LDB(B1, 0, 1); PG8_SCHED; PG8_LDA(At, 0, 0); PG8_STAGE(PG8_SA(1, 1), a1 + hstep, voffA);
;             PG8_WAIT_V(8); PG8_WAIT_L(0); PG8_BAR; PG8_MMA(0, 0, At, B0); PG8_MMA(0, 1, At, B1); PG8_BAR; PG8_SCHED;
;             PG8_LDA(At, 0, 1); PG8_STAGE(PG8_SB(0, 0), b2, voffB); PG8_STAGE(PG8_SB(0, 1), b2 + hstep, voffB); PG8_STAGE(PG8_SA(0, 0), a2, voffA);
;             PG8_WAIT_V(8); PG8_WAIT_L(0); PG8_BAR; PG8_MMA(1, 0, At, B0); PG8_MMA(1, 1, At, B1); PG8_BAR; PG8_SCHED;
.LBB0_683:
	ds_read_b128 v[150:153], v147
	ds_read_b128 v[154:157], v147 offset:1024
	ds_read_b128 v[158:161], v147 offset:2048
	ds_read_b128 v[162:165], v147 offset:3072
	ds_read_b128 v[166:169], v148
	ds_read_b128 v[170:173], v148 offset:1024
	ds_read_b128 v[176:179], v148 offset:2048
	ds_read_b128 v[180:183], v148 offset:3072
	s_add_u32 s26, s24, 0xfffc0080
	s_addc_u32 s27, s25, -1
	s_cmp_eq_u32 s52, 12
	s_cselect_b32 s29, s15, s27
	s_cselect_b32 s28, s48, s26
	s_cselect_b32 s27, s17, s51
	s_cselect_b32 s26, s49, s50
	s_add_i32 m0, s23, 0xc000
	ds_read_b128 v[184:187], v149
	ds_read_b128 v[188:191], v149 offset:1024
	ds_read_b128 v[192:195], v149 offset:2048
	ds_read_b128 v[196:199], v149 offset:3072
	ds_read_b128 v[200:203], v149 offset:4096
	ds_read_b128 v[204:207], v149 offset:5120
	ds_read_b128 v[208:211], v149 offset:6144
	ds_read_b128 v[212:215], v149 offset:7168
	global_load_lds_dwordx4 v136, s[24:25]
	s_add_i32 m0, s23, 0xe000
	s_nop 0
	global_load_lds_dwordx4 v138, s[24:25]
	s_waitcnt vmcnt(8)
	s_waitcnt lgkmcnt(0)
	s_barrier
	s_setprio 1
	s_waitcnt lgkmcnt(0)
	v_mfma_f32_16x16x32_bf16 v[124:127], v[150:153], v[184:187], v[124:127]
	v_mfma_f32_16x16x32_bf16 v[120:123], v[158:161], v[184:187], v[120:123]
	v_mfma_f32_16x16x32_bf16 v[108:111], v[150:153], v[192:195], v[108:111]
	v_mfma_f32_16x16x32_bf16 v[104:107], v[158:161], v[192:195], v[104:107]
	v_mfma_f32_16x16x32_bf16 v[92:95], v[150:153], v[200:203], v[92:95]
	v_mfma_f32_16x16x32_bf16 v[88:91], v[158:161], v[200:203], v[88:91]
	v_mfma_f32_16x16x32_bf16 v[76:79], v[150:153], v[208:211], v[76:79]
	v_mfma_f32_16x16x32_bf16 v[72:75], v[158:161], v[208:211], v[72:75]
	v_mfma_f32_16x16x32_bf16 v[124:127], v[154:157], v[188:191], v[124:127]
	v_mfma_f32_16x16x32_bf16 v[120:123], v[162:165], v[188:191], v[120:123]
	v_mfma_f32_16x16x32_bf16 v[108:111], v[154:157], v[196:199], v[108:111]
	v_mfma_f32_16x16x32_bf16 v[104:107], v[162:165], v[196:199], v[104:107]
	v_mfma_f32_16x16x32_bf16 v[92:95], v[154:157], v[204:207], v[92:95]
	v_mfma_f32_16x16x32_bf16 v[88:91], v[162:165], v[204:207], v[88:91]
	v_mfma_f32_16x16x32_bf16 v[76:79], v[154:157], v[212:215], v[76:79]
	v_mfma_f32_16x16x32_bf16 v[72:75], v[162:165], v[212:215], v[72:75]
	s_setprio 0
	s_setprio 1
	v_mfma_f32_16x16x32_bf16 v[116:119], v[166:169], v[184:187], v[116:119]
	v_mfma_f32_16x16x32_bf16 v[112:115], v[176:179], v[184:187], v[112:115]
	v_mfma_f32_16x16x32_bf16 v[100:103], v[166:169], v[192:195], v[100:103]
	v_mfma_f32_16x16x32_bf16 v[96:99], v[176:179], v[192:195], v[96:99]
	v_mfma_f32_16x16x32_bf16 v[84:87], v[166:169], v[200:203], v[84:87]
	v_mfma_f32_16x16x32_bf16 v[80:83], v[176:179], v[200:203], v[80:83]
	v_mfma_f32_16x16x32_bf16 v[68:71], v[166:169], v[208:211], v[68:71]
	v_mfma_f32_16x16x32_bf16 v[64:67], v[176:179], v[208:211], v[64:67]
	v_mfma_f32_16x16x32_bf16 v[116:119], v[170:173], v[188:191], v[116:119]
	v_mfma_f32_16x16x32_bf16 v[112:115], v[180:183], v[188:191], v[112:115]
	v_mfma_f32_16x16x32_bf16 v[100:103], v[170:173], v[196:199], v[100:103]
	v_mfma_f32_16x16x32_bf16 v[96:99], v[180:183], v[196:199], v[96:99]
	v_mfma_f32_16x16x32_bf16 v[84:87], v[170:173], v[204:207], v[84:87]
	v_mfma_f32_16x16x32_bf16 v[80:83], v[180:183], v[204:207], v[80:83]
	v_mfma_f32_16x16x32_bf16 v[68:71], v[170:173], v[212:215], v[68:71]
	v_mfma_f32_16x16x32_bf16 v[64:67], v[180:183], v[212:215], v[64:67]
	s_setprio 0
	s_barrier
	s_add_i32 s53, s44, s30
	s_mov_b32 m0, s53
	s_nop 0
	global_load_lds_dwordx4 v132, s[26:27]
	s_add_i32 m0, s53, 0x2000
	s_add_u32 s54, s26, 0x40000
	s_addc_u32 s55, s27, 0
	s_add_i32 s53, s45, s30
	global_load_lds_dwordx4 v128, s[26:27]
	s_mov_b32 m0, s53
	s_nop 0
	global_load_lds_dwordx4 v132, s[54:55]
	s_add_i32 m0, s53, 0x2000
	s_nop 0
	global_load_lds_dwordx4 v128, s[54:55]
	s_mov_b32 m0, s23
	s_nop 0
	global_load_lds_dwordx4 v134, s[28:29]
	s_mov_b32 m0, s34
	s_nop 0
	global_load_lds_dwordx4 v130, s[28:29]
	ds_read_b128 v[184:187], v149 offset:16384
	ds_read_b128 v[188:191], v149 offset:17408
	ds_read_b128 v[192:195], v149 offset:18432
	ds_read_b128 v[196:199], v149 offset:19456
	ds_read_b128 v[200:203], v149 offset:20480
	ds_read_b128 v[204:207], v149 offset:21504
	ds_read_b128 v[208:211], v149 offset:22528
	ds_read_b128 v[212:215], v149 offset:23552
	s_waitcnt vmcnt(8)
	s_waitcnt lgkmcnt(0)
	s_barrier
	s_setprio 1
	s_waitcnt lgkmcnt(0)
	v_mfma_f32_16x16x32_bf16 v[60:63], v[150:153], v[184:187], v[60:63]
	v_mfma_f32_16x16x32_bf16 v[56:59], v[158:161], v[184:187], v[56:59]
	v_mfma_f32_16x16x32_bf16 v[44:47], v[150:153], v[192:195], v[44:47]
	v_mfma_f32_16x16x32_bf16 v[40:43], v[158:161], v[192:195], v[40:43]
	v_mfma_f32_16x16x32_bf16 v[28:31], v[150:153], v[200:203], v[28:31]
	v_mfma_f32_16x16x32_bf16 v[24:27], v[158:161], v[200:203], v[24:27]
	v_mfma_f32_16x16x32_bf16 v[12:15], v[150:153], v[208:211], v[12:15]
	v_mfma_f32_16x16x32_bf16 v[8:11], v[158:161], v[208:211], v[8:11]
	v_mfma_f32_16x16x32_bf16 v[60:63], v[154:157], v[188:191], v[60:63]
	v_mfma_f32_16x16x32_bf16 v[56:59], v[162:165], v[188:191], v[56:59]
	v_mfma_f32_16x16x32_bf16 v[44:47], v[154:157], v[196:199], v[44:47]
	v_mfma_f32_16x16x32_bf16 v[40:43], v[162:165], v[196:199], v[40:43]
	v_mfma_f32_16x16x32_bf16 v[28:31], v[154:157], v[204:207], v[28:31]
	v_mfma_f32_16x16x32_bf16 v[24:27], v[162:165], v[204:207], v[24:27]
	v_mfma_f32_16x16x32_bf16 v[12:15], v[154:157], v[212:215], v[12:15]
	v_mfma_f32_16x16x32_bf16 v[8:11], v[162:165], v[212:215], v[8:11]
	s_setprio 0
	s_setprio 1
	v_mfma_f32_16x16x32_bf16 v[52:55], v[166:169], v[184:187], v[52:55]
	v_mfma_f32_16x16x32_bf16 v[48:51], v[176:179], v[184:187], v[48:51]
	v_mfma_f32_16x16x32_bf16 v[36:39], v[166:169], v[192:195], v[36:39]
	v_mfma_f32_16x16x32_bf16 v[32:35], v[176:179], v[192:195], v[32:35]
	v_mfma_f32_16x16x32_bf16 v[20:23], v[166:169], v[200:203], v[20:23]
	v_mfma_f32_16x16x32_bf16 v[16:19], v[176:179], v[200:203], v[16:19]
	v_mfma_f32_16x16x32_bf16 v[4:7], v[166:169], v[208:211], v[4:7]
	v_mfma_f32_16x16x32_bf16 v[0:3], v[176:179], v[208:211], v[0:3]
	v_mfma_f32_16x16x32_bf16 v[52:55], v[170:173], v[188:191], v[52:55]
	v_mfma_f32_16x16x32_bf16 v[48:51], v[180:183], v[188:191], v[48:51]
	v_mfma_f32_16x16x32_bf16 v[36:39], v[170:173], v[196:199], v[36:39]
	v_mfma_f32_16x16x32_bf16 v[32:35], v[180:183], v[196:199], v[32:35]
	v_mfma_f32_16x16x32_bf16 v[20:23], v[170:173], v[204:207], v[20:23]
	v_mfma_f32_16x16x32_bf16 v[16:19], v[180:183], v[204:207], v[16:19]
	v_mfma_f32_16x16x32_bf16 v[4:7], v[170:173], v[212:215], v[4:7]
	v_mfma_f32_16x16x32_bf16 v[0:3], v[180:183], v[212:215], v[0:3]
	s_setprio 0
	s_barrier
; #define PG8_STAGE(bufoff, gbase, voff) do { _Pragma("unroll") for (int _i = 0; _i < 2; ++_i) \
;         __builtin_amdgcn_global_load_lds((const unsigned*)((const char*)(gbase) + (voff)[_i]), (LAS unsigned*)(lds + (bufoff) + ldsw + _i * 8192), 16, 0, 0); } while (0)
; #define PG8_LDA(dst, b, h) do { _Pragma("unroll") for (int m = 0; m < 4; ++m) _Pragma("unroll") for (int k = 0; k < 2; ++k) dst[m][k] = *(const LAS bf16x8*)(lds + PG8_SA(b, h) + aoff + m * 2048 + k * 1024); } while (0)
; #define PG8_LDB(dst, b, h) do { _Pragma("unroll") for (int n = 0; n < 2; ++n) _Pragma("unroll") for (int k = 0; k < 2; ++k) dst[n][k] = *(const LAS bf16x8*)(lds + PG8_SB(b, h) + boff + n * 2048 + k * 1024); } while (0)
; #define PG8_MMA(ai, bj, At, Bt) do { __builtin_amdgcn_s_setprio(1); _Pragma("unroll") for (int m = 0; m < 4; ++m) _Pragma("unroll") for (int n = 0; n < 2; ++n) _Pragma("unroll") for (int k = 0; k < 2; ++k) \
;         acc[ai][bj][m][n] = __builtin_amdgcn_mfma_f32_16x16x32_bf16(Bt[n][k], At[m][k], acc[ai][bj][m][n], 0, 0, 0); __builtin_amdgcn_s_setprio(0); } while (0)
; #define PG8_WAIT_V(n) asm volatile("s_waitcnt vmcnt(" #n ")" ::: "memory")
; #define PG8_WAIT_L(n) asm volatile("s_waitcnt lgkmcnt(" #n ")" ::: "memory")
; #define PG8_BAR __builtin_amdgcn_s_barrier()
; #define PG8_SCHED __builtin_amdgcn_sched_barrier(0)
; template <class Epi, class Sched, bool ALIGN_EPI, bool SP2>
; __device__ __forceinline__ void gemm_phase(LAS unsigned char* lds, const Gemm g, const Sched& S, const Epi& E) {
;     ...
;             PG8_LDB(B0, 1, 0); PG8_LDB(B1, 1, 1); PG8_SCHED; PG8_LDA(At, 1, 0); PG8_STAGE(PG8_SA(0, 1), a2 + hstep, voffA);
;             PG8_WAIT_V(8); PG8_WAIT_L(0); PG8_BAR; PG8_MMA(0, 0, At, B0); PG8_MMA(0, 1, At, B1); PG8_BAR; PG8_SCHED;
;             PG8_LDA(At, 1, 1); PG8_STAGE(PG8_SB(1, 0), b3, voffB); PG8_STAGE(PG8_SB(1, 1), b3 + hstep, voffB); PG8_STAGE(PG8_SA(1, 0), a3, voffA);
;             PG8_WAIT_V(8); PG8_WAIT_L(0); PG8_BAR; PG8_MMA(1, 0, At, B0); PG8_MMA(1, 1, At, B1); PG8_BAR; PG8_SCHED;
	s_add_i32 s53, 0, 0x18000
	s_add_i32 s54, 0, 0x1c000
	v_add_u32_e32 v162, s53, v145
	v_add_u32_e32 v174, s54, v145
	ds_read_b128 v[150:153], v162
	ds_read_b128 v[154:157], v162 offset:1024
	ds_read_b128 v[158:161], v162 offset:2048
	ds_read_b128 v[162:165], v162 offset:3072
	ds_read_b128 v[166:169], v174
	ds_read_b128 v[170:173], v174 offset:1024
	ds_read_b128 v[176:179], v174 offset:2048
	ds_read_b128 v[180:183], v174 offset:3072
	s_add_u32 s28, s28, 0x40000
	s_addc_u32 s29, s29, 0
	s_mov_b32 m0, s35
	ds_read_b128 v[184:187], v149 offset:32768
	ds_read_b128 v[188:191], v149 offset:33792
	ds_read_b128 v[192:195], v149 offset:34816
	ds_read_b128 v[196:199], v149 offset:35840
	ds_read_b128 v[200:203], v149 offset:36864
	ds_read_b128 v[204:207], v149 offset:37888
	ds_read_b128 v[208:211], v149 offset:38912
	ds_read_b128 v[212:215], v149 offset:39936
	global_load_lds_dwordx4 v134, s[28:29]
	s_mov_b32 m0, s36
	s_nop 0
	global_load_lds_dwordx4 v130, s[28:29]
	s_waitcnt vmcnt(8)
	s_waitcnt lgkmcnt(0)
	s_barrier
	s_setprio 1
	s_waitcnt lgkmcnt(0)
	v_mfma_f32_16x16x32_bf16 v[124:127], v[150:153], v[184:187], v[124:127]
	v_mfma_f32_16x16x32_bf16 v[120:123], v[158:161], v[184:187], v[120:123]
	v_mfma_f32_16x16x32_bf16 v[108:111], v[150:153], v[192:195], v[108:111]
	v_mfma_f32_16x16x32_bf16 v[104:107], v[158:161], v[192:195], v[104:107]
	v_mfma_f32_16x16x32_bf16 v[92:95], v[150:153], v[200:203], v[92:95]
	v_mfma_f32_16x16x32_bf16 v[88:91], v[158:161], v[200:203], v[88:91]
	v_mfma_f32_16x16x32_bf16 v[76:79], v[150:153], v[208:211], v[76:79]
	v_mfma_f32_16x16x32_bf16 v[72:75], v[158:161], v[208:211], v[72:75]
	v_mfma_f32_16x16x32_bf16 v[124:127], v[154:157], v[188:191], v[124:127]
	v_mfma_f32_16x16x32_bf16 v[120:123], v[162:165], v[188:191], v[120:123]
	v_mfma_f32_16x16x32_bf16 v[108:111], v[154:157], v[196:199], v[108:111]
	v_mfma_f32_16x16x32_bf16 v[104:107], v[162:165], v[196:199], v[104:107]
	v_mfma_f32_16x16x32_bf16 v[92:95], v[154:157], v[204:207], v[92:95]
	v_mfma_f32_16x16x32_bf16 v[88:91], v[162:165], v[204:207], v[88:91]
	v_mfma_f32_16x16x32_bf16 v[76:79], v[154:157], v[212:215], v[76:79]
	v_mfma_f32_16x16x32_bf16 v[72:75], v[162:165], v[212:215], v[72:75]
	s_setprio 0
	s_setprio 1
	v_mfma_f32_16x16x32_bf16 v[116:119], v[166:169], v[184:187], v[116:119]
	v_mfma_f32_16x16x32_bf16 v[112:115], v[176:179], v[184:187], v[112:115]
	v_mfma_f32_16x16x32_bf16 v[100:103], v[166:169], v[192:195], v[100:103]
	v_mfma_f32_16x16x32_bf16 v[96:99], v[176:179], v[192:195], v[96:99]
	v_mfma_f32_16x16x32_bf16 v[84:87], v[166:169], v[200:203], v[84:87]
	v_mfma_f32_16x16x32_bf16 v[80:83], v[176:179], v[200:203], v[80:83]
	v_mfma_f32_16x16x32_bf16 v[68:71], v[166:169], v[208:211], v[68:71]
	v_mfma_f32_16x16x32_bf16 v[64:67], v[176:179], v[208:211], v[64:67]
	v_mfma_f32_16x16x32_bf16 v[116:119], v[170:173], v[188:191], v[116:119]
	v_mfma_f32_16x16x32_bf16 v[112:115], v[180:183], v[188:191], v[112:115]
	v_mfma_f32_16x16x32_bf16 v[100:103], v[170:173], v[196:199], v[100:103]
	v_mfma_f32_16x16x32_bf16 v[96:99], v[180:183], v[196:199], v[96:99]
	v_mfma_f32_16x16x32_bf16 v[84:87], v[170:173], v[204:207], v[84:87]
	v_mfma_f32_16x16x32_bf16 v[80:83], v[180:183], v[204:207], v[80:83]
	v_mfma_f32_16x16x32_bf16 v[68:71], v[170:173], v[212:215], v[68:71]
	v_mfma_f32_16x16x32_bf16 v[64:67], v[180:183], v[212:215], v[64:67]
	s_setprio 0
	s_barrier
	s_add_u32 s100, s28, 0xfffc0080
	s_addc_u32 s101, s29, -1
	s_add_u32 s98, s26, 0x80
	s_addc_u32 s99, s27, 0
	s_add_i32 s28, s53, s30
	s_mov_b32 m0, s28
	s_nop 0
	global_load_lds_dwordx4 v132, s[98:99]
	s_add_i32 m0, s28, 0x2000
	s_add_u32 s26, s26, 0x40080
	s_addc_u32 s27, s27, 0
	s_add_i32 s28, s54, s30
	global_load_lds_dwordx4 v128, s[98:99]
	s_mov_b32 m0, s28
	s_nop 0
	global_load_lds_dwordx4 v132, s[26:27]
	s_add_i32 m0, s28, 0x2000
	s_nop 0
	global_load_lds_dwordx4 v128, s[26:27]
	s_mov_b32 m0, s38
	s_nop 0
	global_load_lds_dwordx4 v134, s[100:101]
	s_mov_b32 m0, s39
	s_nop 0
	global_load_lds_dwordx4 v130, s[100:101]
	ds_read_b128 v[184:187], v149 offset:49152
	ds_read_b128 v[188:191], v149 offset:50176
	ds_read_b128 v[192:195], v149 offset:51200
	ds_read_b128 v[196:199], v149 offset:52224
	ds_read_b128 v[200:203], v149 offset:53248
	ds_read_b128 v[204:207], v149 offset:54272
	ds_read_b128 v[208:211], v149 offset:55296
	ds_read_b128 v[212:215], v149 offset:56320
	s_waitcnt vmcnt(8)
	s_waitcnt lgkmcnt(0)
	s_barrier
	s_setprio 1
	s_waitcnt lgkmcnt(0)
	v_mfma_f32_16x16x32_bf16 v[60:63], v[150:153], v[184:187], v[60:63]
	v_mfma_f32_16x16x32_bf16 v[56:59], v[158:161], v[184:187], v[56:59]
	v_mfma_f32_16x16x32_bf16 v[44:47], v[150:153], v[192:195], v[44:47]
	v_mfma_f32_16x16x32_bf16 v[40:43], v[158:161], v[192:195], v[40:43]
	v_mfma_f32_16x16x32_bf16 v[28:31], v[150:153], v[200:203], v[28:31]
	v_mfma_f32_16x16x32_bf16 v[24:27], v[158:161], v[200:203], v[24:27]
	v_mfma_f32_16x16x32_bf16 v[12:15], v[150:153], v[208:211], v[12:15]
	v_mfma_f32_16x16x32_bf16 v[8:11], v[158:161], v[208:211], v[8:11]
	v_mfma_f32_16x16x32_bf16 v[60:63], v[154:157], v[188:191], v[60:63]
	v_mfma_f32_16x16x32_bf16 v[56:59], v[162:165], v[188:191], v[56:59]
	v_mfma_f32_16x16x32_bf16 v[44:47], v[154:157], v[196:199], v[44:47]
	v_mfma_f32_16x16x32_bf16 v[40:43], v[162:165], v[196:199], v[40:43]
	v_mfma_f32_16x16x32_bf16 v[28:31], v[154:157], v[204:207], v[28:31]
	v_mfma_f32_16x16x32_bf16 v[24:27], v[162:165], v[204:207], v[24:27]
	v_mfma_f32_16x16x32_bf16 v[12:15], v[154:157], v[212:215], v[12:15]
	v_mfma_f32_16x16x32_bf16 v[8:11], v[162:165], v[212:215], v[8:11]
	s_setprio 0
	s_setprio 1
	v_mfma_f32_16x16x32_bf16 v[52:55], v[166:169], v[184:187], v[52:55]
	v_mfma_f32_16x16x32_bf16 v[48:51], v[176:179], v[184:187], v[48:51]
	v_mfma_f32_16x16x32_bf16 v[36:39], v[166:169], v[192:195], v[36:39]
	v_mfma_f32_16x16x32_bf16 v[32:35], v[176:179], v[192:195], v[32:35]
	v_mfma_f32_16x16x32_bf16 v[20:23], v[166:169], v[200:203], v[20:23]
	v_mfma_f32_16x16x32_bf16 v[16:19], v[176:179], v[200:203], v[16:19]
	v_mfma_f32_16x16x32_bf16 v[4:7], v[166:169], v[208:211], v[4:7]
	v_mfma_f32_16x16x32_bf16 v[0:3], v[176:179], v[208:211], v[0:3]
	v_mfma_f32_16x16x32_bf16 v[52:55], v[170:173], v[188:191], v[52:55]
	v_mfma_f32_16x16x32_bf16 v[48:51], v[180:183], v[188:191], v[48:51]
	v_mfma_f32_16x16x32_bf16 v[36:39], v[170:173], v[196:199], v[36:39]
	v_mfma_f32_16x16x32_bf16 v[32:35], v[180:183], v[196:199], v[32:35]
	v_mfma_f32_16x16x32_bf16 v[20:23], v[170:173], v[204:207], v[20:23]
	v_mfma_f32_16x16x32_bf16 v[16:19], v[180:183], v[204:207], v[16:19]
	v_mfma_f32_16x16x32_bf16 v[4:7], v[170:173], v[212:215], v[4:7]
	v_mfma_f32_16x16x32_bf16 v[0:3], v[180:183], v[212:215], v[0:3]
	s_setprio 0
	s_barrier
	s_add_i32 s52, s52, 2
	s_add_u32 s24, s24, 0x100
	s_addc_u32 s25, s25, 0
	s_add_u32 s50, s50, 0x100
	s_addc_u32 s51, s51, 0
	s_cmp_gt_u32 s52, 13
	s_cbranch_scc0 .LBB0_683
	s_and_b64 vcc, exec, s[12:13]
	s_cbranch_vccz .LBB0_686
	s_barrier

; #define PG8_STAGE(bufoff, gbase, voff) do { _Pragma("unroll") for (int _i = 0; _i < 2; ++_i) \
;         __builtin_amdgcn_global_load_lds((const unsigned*)((const char*)(gbase) + (voff)[_i]), (LAS unsigned*)(lds + (bufoff) + ldsw + _i * 8192), 16, 0, 0); } while (0)
; #define PG8_LDA(dst, b, h) do { _Pragma("unroll") for (int m = 0; m < 4; ++m) _Pragma("unroll") for (int k = 0; k < 2; ++k) dst[m][k] = *(const LAS bf16x8*)(lds + PG8_SA(b, h) + aoff + m * 2048 + k * 1024); } while (0)
; #define PG8_LDB(dst, b, h) do { _Pragma("unroll") for (int n = 0; n < 2; ++n) _Pragma("unroll") for (int k = 0; k < 2; ++k) dst[n][k] = *(const LAS bf16x8*)(lds + PG8_SB(b, h) + boff + n * 2048 + k * 1024); } while (0)
; #define PG8_MMA(ai, bj, At, Bt) do { __builtin_amdgcn_s_setprio(1); _Pragma("unroll") for (int m = 0; m < 4; ++m) _Pragma("unroll") for (int n = 0; n < 2; ++n) _Pragma("unroll") for (int k = 0; k < 2; ++k) \
;         acc[ai][bj][m][n] = __builtin_amdgcn_mfma_f32_16x16x32_bf16(Bt[n][k], At[m][k], acc[ai][bj][m][n], 0, 0, 0); __builtin_amdgcn_s_setprio(0); } while (0)
; #define PG8_WAIT_V(n) asm volatile("s_waitcnt vmcnt(" #n ")" ::: "memory")
; #define PG8_WAIT_L(n) asm volatile("s_waitcnt lgkmcnt(" #n ")" ::: "memory")
; #define PG8_BAR __builtin_amdgcn_s_barrier()
; #define PG8_SCHED __builtin_amdgcn_sched_barrier(0)
; template <class Epi, class Sched, bool ALIGN_EPI, bool SP2>
; __device__ __forceinline__ void gemm_phase(LAS unsigned char* lds, const Gemm g, const Sched& S, const Epi& E) {
;     ...
;             PG8_LDB(B0, 0, 0); PG8_LDB(B1, 0, 1); PG8_SCHED; PG8_LDA(At, 0, 0); PG8_STAGE(PG8_SA(1, 1), a1 + hstep, voffA);
;             PG8_WAIT_V(8); PG8_WAIT_L(0); PG8_BAR; PG8_MMA(0, 0, At, B0); PG8_MMA(0, 1, At, B1); PG8_BAR; PG8_SCHED;
;             PG8_LDA(At, 0, 1); PG8_STAGE(PG8_SB(0, 0), b2, voffB); PG8_STAGE(PG8_SB(0, 1), b2 + hstep, voffB); PG8_STAGE(PG8_SA(0, 0), a2, voffA);
;             PG8_WAIT_V(8); PG8_WAIT_L(0); PG8_BAR; PG8_MMA(1, 0, At, B0); PG8_MMA(1, 1, At, B1); PG8_BAR; PG8_SCHED;
.LBB0_766:
	ds_read_b128 v[120:123], v169
	ds_read_b128 v[124:127], v169 offset:1024
	ds_read_b128 v[136:139], v169 offset:2048
	ds_read_b128 v[140:143], v169 offset:3072
	ds_read_b128 v[160:163], v170
	ds_read_b128 v[172:175], v170 offset:1024
	ds_read_b128 v[176:179], v170 offset:2048
	ds_read_b128 v[180:183], v170 offset:3072
	s_add_u32 s26, s24, 0x100
	s_addc_u32 s27, s25, 0
	s_cmp_eq_u32 s56, 40
	s_cselect_b32 s31, s5, s27
	s_cselect_b32 s30, s4, s26
	s_cselect_b32 s29, s23, s55
	s_cselect_b32 s28, s22, s54
	s_add_i32 m0, s37, 0xc000
	ds_read_b128 v[184:187], v171
	ds_read_b128 v[188:191], v171 offset:1024
	ds_read_b128 v[192:195], v171 offset:2048
	ds_read_b128 v[196:199], v171 offset:3072
	ds_read_b128 v[200:203], v171 offset:4096
	ds_read_b128 v[204:207], v171 offset:5120
	ds_read_b128 v[208:211], v171 offset:6144
	ds_read_b128 v[212:215], v171 offset:7168
	global_load_lds_dwordx4 v152, s[24:25]
	s_add_i32 m0, s37, 0xe000
	s_nop 0
	global_load_lds_dwordx4 v154, s[24:25]
	s_waitcnt vmcnt(8)
	s_waitcnt lgkmcnt(0)
	s_barrier
	s_setprio 1
	s_waitcnt lgkmcnt(0)
	v_mfma_f32_16x16x32_bf16 v[132:135], v[120:123], v[184:187], v[132:135]
	v_mfma_f32_16x16x32_bf16 v[128:131], v[136:139], v[184:187], v[128:131]
	v_mfma_f32_16x16x32_bf16 v[108:111], v[120:123], v[192:195], v[108:111]
	v_mfma_f32_16x16x32_bf16 v[104:107], v[136:139], v[192:195], v[104:107]
	v_mfma_f32_16x16x32_bf16 v[92:95], v[120:123], v[200:203], v[92:95]
	v_mfma_f32_16x16x32_bf16 v[88:91], v[136:139], v[200:203], v[88:91]
	v_mfma_f32_16x16x32_bf16 v[76:79], v[120:123], v[208:211], v[76:79]
	v_mfma_f32_16x16x32_bf16 v[72:75], v[136:139], v[208:211], v[72:75]
	v_mfma_f32_16x16x32_bf16 v[132:135], v[124:127], v[188:191], v[132:135]
	v_mfma_f32_16x16x32_bf16 v[128:131], v[140:143], v[188:191], v[128:131]
	v_mfma_f32_16x16x32_bf16 v[108:111], v[124:127], v[196:199], v[108:111]
	v_mfma_f32_16x16x32_bf16 v[104:107], v[140:143], v[196:199], v[104:107]
	v_mfma_f32_16x16x32_bf16 v[92:95], v[124:127], v[204:207], v[92:95]
	v_mfma_f32_16x16x32_bf16 v[88:91], v[140:143], v[204:207], v[88:91]
	v_mfma_f32_16x16x32_bf16 v[76:79], v[124:127], v[212:215], v[76:79]
	v_mfma_f32_16x16x32_bf16 v[72:75], v[140:143], v[212:215], v[72:75]
	s_setprio 0
	s_setprio 1
	v_mfma_f32_16x16x32_bf16 v[116:119], v[160:163], v[184:187], v[116:119]
	v_mfma_f32_16x16x32_bf16 v[112:115], v[176:179], v[184:187], v[112:115]
	v_mfma_f32_16x16x32_bf16 v[100:103], v[160:163], v[192:195], v[100:103]
	v_mfma_f32_16x16x32_bf16 v[96:99], v[176:179], v[192:195], v[96:99]
	v_mfma_f32_16x16x32_bf16 v[84:87], v[160:163], v[200:203], v[84:87]
	v_mfma_f32_16x16x32_bf16 v[80:83], v[176:179], v[200:203], v[80:83]
	v_mfma_f32_16x16x32_bf16 v[68:71], v[160:163], v[208:211], v[68:71]
	v_mfma_f32_16x16x32_bf16 v[64:67], v[176:179], v[208:211], v[64:67]
	v_mfma_f32_16x16x32_bf16 v[116:119], v[172:175], v[188:191], v[116:119]
	v_mfma_f32_16x16x32_bf16 v[112:115], v[180:183], v[188:191], v[112:115]
	v_mfma_f32_16x16x32_bf16 v[100:103], v[172:175], v[196:199], v[100:103]
	v_mfma_f32_16x16x32_bf16 v[96:99], v[180:183], v[196:199], v[96:99]
	v_mfma_f32_16x16x32_bf16 v[84:87], v[172:175], v[204:207], v[84:87]
	v_mfma_f32_16x16x32_bf16 v[80:83], v[180:183], v[204:207], v[80:83]
	v_mfma_f32_16x16x32_bf16 v[68:71], v[172:175], v[212:215], v[68:71]
	v_mfma_f32_16x16x32_bf16 v[64:67], v[180:183], v[212:215], v[64:67]
	s_setprio 0
	s_barrier
	s_add_i32 s24, s48, s36
	s_mov_b32 m0, s24
	s_nop 0
	global_load_lds_dwordx4 v146, s[28:29]
	s_add_i32 m0, s24, 0x2000
	s_add_u32 s24, s28, 0xb0000
	s_addc_u32 s25, s29, 0
	s_add_i32 s57, s49, s36
	global_load_lds_dwordx4 v150, s[28:29]
	s_mov_b32 m0, s57
	s_nop 0
	global_load_lds_dwordx4 v146, s[24:25]
	s_add_i32 m0, s57, 0x2000
	s_nop 0
	global_load_lds_dwordx4 v150, s[24:25]
	s_mov_b32 m0, s37
	s_nop 0
	global_load_lds_dwordx4 v144, s[30:31]
	s_mov_b32 m0, s38
	s_nop 0
	global_load_lds_dwordx4 v148, s[30:31]
	ds_read_b128 v[184:187], v171 offset:16384
	ds_read_b128 v[188:191], v171 offset:17408
	ds_read_b128 v[192:195], v171 offset:18432
	ds_read_b128 v[196:199], v171 offset:19456
	ds_read_b128 v[200:203], v171 offset:20480
	ds_read_b128 v[204:207], v171 offset:21504
	ds_read_b128 v[208:211], v171 offset:22528
	ds_read_b128 v[212:215], v171 offset:23552
	s_waitcnt vmcnt(8)
	s_waitcnt lgkmcnt(0)
	s_barrier
	s_setprio 1
	s_waitcnt lgkmcnt(0)
	v_mfma_f32_16x16x32_bf16 v[60:63], v[120:123], v[184:187], v[60:63]
	v_mfma_f32_16x16x32_bf16 v[56:59], v[136:139], v[184:187], v[56:59]
	v_mfma_f32_16x16x32_bf16 v[44:47], v[120:123], v[192:195], v[44:47]
	v_mfma_f32_16x16x32_bf16 v[40:43], v[136:139], v[192:195], v[40:43]
	v_mfma_f32_16x16x32_bf16 v[28:31], v[120:123], v[200:203], v[28:31]
	v_mfma_f32_16x16x32_bf16 v[24:27], v[136:139], v[200:203], v[24:27]
	v_mfma_f32_16x16x32_bf16 v[12:15], v[120:123], v[208:211], v[12:15]
	v_mfma_f32_16x16x32_bf16 v[8:11], v[136:139], v[208:211], v[8:11]
	v_mfma_f32_16x16x32_bf16 v[60:63], v[124:127], v[188:191], v[60:63]
	v_mfma_f32_16x16x32_bf16 v[56:59], v[140:143], v[188:191], v[56:59]
	v_mfma_f32_16x16x32_bf16 v[44:47], v[124:127], v[196:199], v[44:47]
	v_mfma_f32_16x16x32_bf16 v[40:43], v[140:143], v[196:199], v[40:43]
	v_mfma_f32_16x16x32_bf16 v[28:31], v[124:127], v[204:207], v[28:31]
	v_mfma_f32_16x16x32_bf16 v[24:27], v[140:143], v[204:207], v[24:27]
	v_mfma_f32_16x16x32_bf16 v[12:15], v[124:127], v[212:215], v[12:15]
	v_mfma_f32_16x16x32_bf16 v[8:11], v[140:143], v[212:215], v[8:11]
	s_setprio 0
	s_setprio 1
	v_mfma_f32_16x16x32_bf16 v[52:55], v[160:163], v[184:187], v[52:55]
	v_mfma_f32_16x16x32_bf16 v[48:51], v[176:179], v[184:187], v[48:51]
	v_mfma_f32_16x16x32_bf16 v[36:39], v[160:163], v[192:195], v[36:39]
	v_mfma_f32_16x16x32_bf16 v[32:35], v[176:179], v[192:195], v[32:35]
	v_mfma_f32_16x16x32_bf16 v[20:23], v[160:163], v[200:203], v[20:23]
	v_mfma_f32_16x16x32_bf16 v[16:19], v[176:179], v[200:203], v[16:19]
	v_mfma_f32_16x16x32_bf16 v[4:7], v[160:163], v[208:211], v[4:7]
	v_mfma_f32_16x16x32_bf16 v[0:3], v[176:179], v[208:211], v[0:3]
	v_mfma_f32_16x16x32_bf16 v[52:55], v[172:175], v[188:191], v[52:55]
	v_mfma_f32_16x16x32_bf16 v[48:51], v[180:183], v[188:191], v[48:51]
	v_mfma_f32_16x16x32_bf16 v[36:39], v[172:175], v[196:199], v[36:39]
	v_mfma_f32_16x16x32_bf16 v[32:35], v[180:183], v[196:199], v[32:35]
	v_mfma_f32_16x16x32_bf16 v[20:23], v[172:175], v[204:207], v[20:23]
	v_mfma_f32_16x16x32_bf16 v[16:19], v[180:183], v[204:207], v[16:19]
	v_mfma_f32_16x16x32_bf16 v[4:7], v[172:175], v[212:215], v[4:7]
	v_mfma_f32_16x16x32_bf16 v[0:3], v[180:183], v[212:215], v[0:3]
	s_setprio 0
	s_barrier
; #define PG8_STAGE(bufoff, gbase, voff) do { _Pragma("unroll") for (int _i = 0; _i < 2; ++_i) \
;         __builtin_amdgcn_global_load_lds((const unsigned*)((const char*)(gbase) + (voff)[_i]), (LAS unsigned*)(lds + (bufoff) + ldsw + _i * 8192), 16, 0, 0); } while (0)
; #define PG8_LDA(dst, b, h) do { _Pragma("unroll") for (int m = 0; m < 4; ++m) _Pragma("unroll") for (int k = 0; k < 2; ++k) dst[m][k] = *(const LAS bf16x8*)(lds + PG8_SA(b, h) + aoff + m * 2048 + k * 1024); } while (0)
; #define PG8_LDB(dst, b, h) do { _Pragma("unroll") for (int n = 0; n < 2; ++n) _Pragma("unroll") for (int k = 0; k < 2; ++k) dst[n][k] = *(const LAS bf16x8*)(lds + PG8_SB(b, h) + boff + n * 2048 + k * 1024); } while (0)
; #define PG8_MMA(ai, bj, At, Bt) do { __builtin_amdgcn_s_setprio(1); _Pragma("unroll") for (int m = 0; m < 4; ++m) _Pragma("unroll") for (int n = 0; n < 2; ++n) _Pragma("unroll") for (int k = 0; k < 2; ++k) \
;         acc[ai][bj][m][n] = __builtin_amdgcn_mfma_f32_16x16x32_bf16(Bt[n][k], At[m][k], acc[ai][bj][m][n], 0, 0, 0); __builtin_amdgcn_s_setprio(0); } while (0)
; #define PG8_WAIT_V(n) asm volatile("s_waitcnt vmcnt(" #n ")" ::: "memory")
; #define PG8_WAIT_L(n) asm volatile("s_waitcnt lgkmcnt(" #n ")" ::: "memory")
; #define PG8_BAR __builtin_amdgcn_s_barrier()
; #define PG8_SCHED __builtin_amdgcn_sched_barrier(0)
; template <class Epi, class Sched, bool ALIGN_EPI, bool SP2>
; __device__ __forceinline__ void gemm_phase(LAS unsigned char* lds, const Gemm g, const Sched& S, const Epi& E) {
;     ...
;             PG8_LDB(B0, 1, 0); PG8_LDB(B1, 1, 1); PG8_SCHED; PG8_LDA(At, 1, 0); PG8_STAGE(PG8_SA(0, 1), a2 + hstep, voffA);
;             PG8_WAIT_V(8); PG8_WAIT_L(0); PG8_BAR; PG8_MMA(0, 0, At, B0); PG8_MMA(0, 1, At, B1); PG8_BAR; PG8_SCHED;
;             PG8_LDA(At, 1, 1); PG8_STAGE(PG8_SB(1, 0), b3, voffB); PG8_STAGE(PG8_SB(1, 1), b3 + hstep, voffB); PG8_STAGE(PG8_SA(1, 0), a3, voffA);
;             PG8_WAIT_V(8); PG8_WAIT_L(0); PG8_BAR; PG8_MMA(1, 0, At, B0); PG8_MMA(1, 1, At, B1); PG8_BAR; PG8_SCHED;
	s_add_i32 s57, 0, 0x18000
	s_add_i32 s58, 0, 0x1c000
	v_add_u32_e32 v140, s57, v167
	v_add_u32_e32 v180, s58, v167
	ds_read_b128 v[120:123], v140
	ds_read_b128 v[124:127], v140 offset:1024
	ds_read_b128 v[136:139], v140 offset:2048
	ds_read_b128 v[140:143], v140 offset:3072
	ds_read_b128 v[160:163], v180
	ds_read_b128 v[172:175], v180 offset:1024
	ds_read_b128 v[176:179], v180 offset:2048
	ds_read_b128 v[180:183], v180 offset:3072
	s_add_u32 s24, s30, 0xb0000
	s_addc_u32 s25, s31, 0
	s_mov_b32 m0, s39
	ds_read_b128 v[184:187], v171 offset:32768
	ds_read_b128 v[188:191], v171 offset:33792
	ds_read_b128 v[192:195], v171 offset:34816
	ds_read_b128 v[196:199], v171 offset:35840
	ds_read_b128 v[200:203], v171 offset:36864
	ds_read_b128 v[204:207], v171 offset:37888
	ds_read_b128 v[208:211], v171 offset:38912
	ds_read_b128 v[212:215], v171 offset:39936
	global_load_lds_dwordx4 v144, s[24:25]
	s_mov_b32 m0, s40
	s_nop 0
	global_load_lds_dwordx4 v148, s[24:25]
	s_waitcnt vmcnt(8)
	s_waitcnt lgkmcnt(0)
	s_barrier
	s_setprio 1
	s_waitcnt lgkmcnt(0)
	v_mfma_f32_16x16x32_bf16 v[132:135], v[120:123], v[184:187], v[132:135]
	v_mfma_f32_16x16x32_bf16 v[128:131], v[136:139], v[184:187], v[128:131]
	v_mfma_f32_16x16x32_bf16 v[108:111], v[120:123], v[192:195], v[108:111]
	v_mfma_f32_16x16x32_bf16 v[104:107], v[136:139], v[192:195], v[104:107]
	v_mfma_f32_16x16x32_bf16 v[92:95], v[120:123], v[200:203], v[92:95]
	v_mfma_f32_16x16x32_bf16 v[88:91], v[136:139], v[200:203], v[88:91]
	v_mfma_f32_16x16x32_bf16 v[76:79], v[120:123], v[208:211], v[76:79]
	v_mfma_f32_16x16x32_bf16 v[72:75], v[136:139], v[208:211], v[72:75]
	v_mfma_f32_16x16x32_bf16 v[132:135], v[124:127], v[188:191], v[132:135]
	v_mfma_f32_16x16x32_bf16 v[128:131], v[140:143], v[188:191], v[128:131]
	v_mfma_f32_16x16x32_bf16 v[108:111], v[124:127], v[196:199], v[108:111]
	v_mfma_f32_16x16x32_bf16 v[104:107], v[140:143], v[196:199], v[104:107]
	v_mfma_f32_16x16x32_bf16 v[92:95], v[124:127], v[204:207], v[92:95]
	v_mfma_f32_16x16x32_bf16 v[88:91], v[140:143], v[204:207], v[88:91]
	v_mfma_f32_16x16x32_bf16 v[76:79], v[124:127], v[212:215], v[76:79]
	v_mfma_f32_16x16x32_bf16 v[72:75], v[140:143], v[212:215], v[72:75]
	s_setprio 0
	s_setprio 1
	v_mfma_f32_16x16x32_bf16 v[116:119], v[160:163], v[184:187], v[116:119]
	v_mfma_f32_16x16x32_bf16 v[112:115], v[176:179], v[184:187], v[112:115]
	v_mfma_f32_16x16x32_bf16 v[100:103], v[160:163], v[192:195], v[100:103]
	v_mfma_f32_16x16x32_bf16 v[96:99], v[176:179], v[192:195], v[96:99]
	v_mfma_f32_16x16x32_bf16 v[84:87], v[160:163], v[200:203], v[84:87]
	v_mfma_f32_16x16x32_bf16 v[80:83], v[176:179], v[200:203], v[80:83]
	v_mfma_f32_16x16x32_bf16 v[68:71], v[160:163], v[208:211], v[68:71]
	v_mfma_f32_16x16x32_bf16 v[64:67], v[176:179], v[208:211], v[64:67]
	v_mfma_f32_16x16x32_bf16 v[116:119], v[172:175], v[188:191], v[116:119]
	v_mfma_f32_16x16x32_bf16 v[112:115], v[180:183], v[188:191], v[112:115]
	v_mfma_f32_16x16x32_bf16 v[100:103], v[172:175], v[196:199], v[100:103]
	v_mfma_f32_16x16x32_bf16 v[96:99], v[180:183], v[196:199], v[96:99]
	v_mfma_f32_16x16x32_bf16 v[84:87], v[172:175], v[204:207], v[84:87]
	v_mfma_f32_16x16x32_bf16 v[80:83], v[180:183], v[204:207], v[80:83]
	v_mfma_f32_16x16x32_bf16 v[68:71], v[172:175], v[212:215], v[68:71]
	v_mfma_f32_16x16x32_bf16 v[64:67], v[180:183], v[212:215], v[64:67]
	s_setprio 0
	s_barrier
	s_add_u32 s100, s24, 0xfff50080
	s_addc_u32 s101, s25, -1
	s_add_u32 s98, s28, 0x80
	s_addc_u32 s99, s29, 0
	s_add_i32 s24, s57, s36
	s_mov_b32 m0, s24
	s_nop 0
	global_load_lds_dwordx4 v146, s[98:99]
	s_add_i32 m0, s24, 0x2000
	s_add_u32 s24, s28, 0xb0080
	s_addc_u32 s25, s29, 0
	s_add_i32 s28, s58, s36
	global_load_lds_dwordx4 v150, s[98:99]
	s_mov_b32 m0, s28
	s_nop 0
	global_load_lds_dwordx4 v146, s[24:25]
	s_add_i32 m0, s28, 0x2000
	s_nop 0
	global_load_lds_dwordx4 v150, s[24:25]
	s_mov_b32 m0, s45
	s_nop 0
	global_load_lds_dwordx4 v144, s[100:101]
	s_mov_b32 m0, s46
	s_nop 0
	global_load_lds_dwordx4 v148, s[100:101]
	ds_read_b128 v[184:187], v171 offset:49152
	ds_read_b128 v[188:191], v171 offset:50176
	ds_read_b128 v[192:195], v171 offset:51200
	ds_read_b128 v[196:199], v171 offset:52224
	ds_read_b128 v[200:203], v171 offset:53248
	ds_read_b128 v[204:207], v171 offset:54272
	ds_read_b128 v[208:211], v171 offset:55296
	ds_read_b128 v[212:215], v171 offset:56320
	s_waitcnt vmcnt(8)
	s_waitcnt lgkmcnt(0)
	s_barrier
	s_setprio 1
	s_waitcnt lgkmcnt(0)
	v_mfma_f32_16x16x32_bf16 v[60:63], v[120:123], v[184:187], v[60:63]
	v_mfma_f32_16x16x32_bf16 v[56:59], v[136:139], v[184:187], v[56:59]
	v_mfma_f32_16x16x32_bf16 v[44:47], v[120:123], v[192:195], v[44:47]
	v_mfma_f32_16x16x32_bf16 v[40:43], v[136:139], v[192:195], v[40:43]
	v_mfma_f32_16x16x32_bf16 v[28:31], v[120:123], v[200:203], v[28:31]
	v_mfma_f32_16x16x32_bf16 v[24:27], v[136:139], v[200:203], v[24:27]
	v_mfma_f32_16x16x32_bf16 v[12:15], v[120:123], v[208:211], v[12:15]
	v_mfma_f32_16x16x32_bf16 v[8:11], v[136:139], v[208:211], v[8:11]
	v_mfma_f32_16x16x32_bf16 v[60:63], v[124:127], v[188:191], v[60:63]
	v_mfma_f32_16x16x32_bf16 v[56:59], v[140:143], v[188:191], v[56:59]
	v_mfma_f32_16x16x32_bf16 v[44:47], v[124:127], v[196:199], v[44:47]
	v_mfma_f32_16x16x32_bf16 v[40:43], v[140:143], v[196:199], v[40:43]
	v_mfma_f32_16x16x32_bf16 v[28:31], v[124:127], v[204:207], v[28:31]
	v_mfma_f32_16x16x32_bf16 v[24:27], v[140:143], v[204:207], v[24:27]
	v_mfma_f32_16x16x32_bf16 v[12:15], v[124:127], v[212:215], v[12:15]
	v_mfma_f32_16x16x32_bf16 v[8:11], v[140:143], v[212:215], v[8:11]
	s_setprio 0
	s_setprio 1
	v_mfma_f32_16x16x32_bf16 v[52:55], v[160:163], v[184:187], v[52:55]
	v_mfma_f32_16x16x32_bf16 v[48:51], v[176:179], v[184:187], v[48:51]
	v_mfma_f32_16x16x32_bf16 v[36:39], v[160:163], v[192:195], v[36:39]
	v_mfma_f32_16x16x32_bf16 v[32:35], v[176:179], v[192:195], v[32:35]
	v_mfma_f32_16x16x32_bf16 v[20:23], v[160:163], v[200:203], v[20:23]
	v_mfma_f32_16x16x32_bf16 v[16:19], v[176:179], v[200:203], v[16:19]
	v_mfma_f32_16x16x32_bf16 v[4:7], v[160:163], v[208:211], v[4:7]
	v_mfma_f32_16x16x32_bf16 v[0:3], v[176:179], v[208:211], v[0:3]
	v_mfma_f32_16x16x32_bf16 v[52:55], v[172:175], v[188:191], v[52:55]
	v_mfma_f32_16x16x32_bf16 v[48:51], v[180:183], v[188:191], v[48:51]
	v_mfma_f32_16x16x32_bf16 v[36:39], v[172:175], v[196:199], v[36:39]
	v_mfma_f32_16x16x32_bf16 v[32:35], v[180:183], v[196:199], v[32:35]
	v_mfma_f32_16x16x32_bf16 v[20:23], v[172:175], v[204:207], v[20:23]
	v_mfma_f32_16x16x32_bf16 v[16:19], v[180:183], v[204:207], v[16:19]
	v_mfma_f32_16x16x32_bf16 v[4:7], v[172:175], v[212:215], v[4:7]
	v_mfma_f32_16x16x32_bf16 v[0:3], v[180:183], v[212:215], v[0:3]
	s_setprio 0
	s_barrier
	s_add_i32 s56, s56, 2
	s_add_u32 s54, s54, 0x100
	s_addc_u32 s55, s55, 0
	s_cmp_gt_u32 s56, 41
	s_mov_b64 s[24:25], s[26:27]
	s_cbranch_scc0 .LBB0_766
	s_and_b64 vcc, exec, s[12:13]
	s_cbranch_vccz .LBB0_769
	s_barrier
